# prologue inputs and final LayerNorm rows (read once by one wave) loaded non-temporal
# speedup vs baseline: 1.1476x; 1.0111x over previous
; __device__ __forceinline__ void p0_load(const TDesc& d, float (&wv)[32], int lane) {
;     const int nblk = d.N / 32, kb = d.item / nblk, nb = d.item % nblk, k0 = 64 * kb, n0 = 32 * nb;
; #pragma unroll
;     for (int i = 0; i < 32; ++i) wv[i] = d.W[(size_t)(k0 + 2 * i + (lane >> 5)) * d.N + n0 + (lane & 31)];
; }
.LBB0_78:
	s_lshr_b32 s36, s33, 5
	v_cvt_f32_i32_e32 v5, s36
	s_sext_i32_i16 s58, s63
	v_cvt_f32_i32_e32 v40, s58
	s_ashr_i32 s58, s58, 30
	v_rcp_iflag_f32_e32 v41, v5
	s_or_b32 s60, s58, 1
	v_mul_f32_e32 v41, v40, v41
	v_trunc_f32_e32 v41, v41
	v_fma_f32 v40, -v41, v5, v40
	v_cvt_i32_f32_e32 v41, v41
	v_cmp_ge_f32_e64 s[58:59], |v40|, v5
	s_and_b64 s[58:59], s[58:59], exec
	s_cselect_b32 s58, s60, 0
	v_readfirstlane_b32 s59, v41
	s_add_i32 s58, s59, s58
	s_sext_i32_i16 s62, s58
	s_mul_i32 s58, s58, s36
	s_sub_i32 s36, s63, s58
	s_sext_i32_i16 s36, s36
	s_lshl_b32 s58, s36, 5
	s_ashr_i32 s59, s58, 31
	s_lshl_b32 s60, s62, 6
	s_lshl_b64 s[64:65], s[58:59], 2
	s_add_u32 s4, s4, s64
	v_add_u32_e32 v72, s60, v76
	s_addc_u32 s5, s5, s65
	v_lshl_add_u64 v[64:65], s[4:5], 0, v[6:7]
	v_mad_u64_u32 v[40:41], s[4:5], v72, s33, 0
	v_ashrrev_i32_e32 v73, 31, v72
	v_mov_b32_e32 v42, v41
	v_mad_u64_u32 v[42:43], s[4:5], v73, s33, v[42:43]
	v_add_u32_e32 v5, 2, v72
	v_mov_b32_e32 v41, v42
	v_mad_u64_u32 v[42:43], s[4:5], v5, s33, 0
	v_ashrrev_i32_e32 v45, 31, v5
	v_mov_b32_e32 v44, v43
	v_mad_u64_u32 v[44:45], s[4:5], v45, s33, v[44:45]
	v_add_u32_e32 v5, 4, v72
	v_mov_b32_e32 v43, v44
	v_mad_u64_u32 v[44:45], s[4:5], v5, s33, 0
	v_ashrrev_i32_e32 v47, 31, v5
	v_mov_b32_e32 v46, v45
	v_mad_u64_u32 v[46:47], s[4:5], v47, s33, v[46:47]
	v_add_u32_e32 v5, 6, v72
	v_mov_b32_e32 v45, v46
	v_mad_u64_u32 v[46:47], s[4:5], v5, s33, 0
	v_ashrrev_i32_e32 v49, 31, v5
	v_mov_b32_e32 v48, v47
	v_mad_u64_u32 v[48:49], s[4:5], v49, s33, v[48:49]
	v_add_u32_e32 v5, 8, v72
	v_mov_b32_e32 v47, v48
	v_mad_u64_u32 v[48:49], s[4:5], v5, s33, 0
	v_ashrrev_i32_e32 v51, 31, v5
	v_mov_b32_e32 v50, v49
	v_mad_u64_u32 v[50:51], s[4:5], v51, s33, v[50:51]
	v_add_u32_e32 v5, 10, v72
	v_mov_b32_e32 v49, v50
	v_mad_u64_u32 v[50:51], s[4:5], v5, s33, 0
	v_ashrrev_i32_e32 v53, 31, v5
	v_mov_b32_e32 v52, v51
	v_mad_u64_u32 v[52:53], s[4:5], v53, s33, v[52:53]
	v_add_u32_e32 v5, 12, v72
	v_mov_b32_e32 v51, v52
	v_mad_u64_u32 v[52:53], s[4:5], v5, s33, 0
	v_ashrrev_i32_e32 v55, 31, v5
	v_mov_b32_e32 v54, v53
	v_mad_u64_u32 v[54:55], s[4:5], v55, s33, v[54:55]
	v_add_u32_e32 v5, 14, v72
	v_mov_b32_e32 v53, v54
	v_mad_u64_u32 v[54:55], s[4:5], v5, s33, 0
	v_ashrrev_i32_e32 v57, 31, v5
	v_mov_b32_e32 v56, v55
	v_mad_u64_u32 v[56:57], s[4:5], v57, s33, v[56:57]
	v_lshl_add_u64 v[40:41], v[40:41], 2, v[64:65]
	v_lshl_add_u64 v[42:43], v[42:43], 2, v[64:65]
	v_lshl_add_u64 v[44:45], v[44:45], 2, v[64:65]
	v_lshl_add_u64 v[46:47], v[46:47], 2, v[64:65]
	v_lshl_add_u64 v[48:49], v[48:49], 2, v[64:65]
	v_mov_b32_e32 v55, v56
	v_add_u32_e32 v5, 16, v72
	v_lshl_add_u64 v[50:51], v[50:51], 2, v[64:65]
	v_lshl_add_u64 v[52:53], v[52:53], 2, v[64:65]
	v_lshl_add_u64 v[54:55], v[54:55], 2, v[64:65]
	global_load_dword v40, v[40:41], off nt
	s_nop 0
	global_load_dword v41, v[42:43], off nt
	s_nop 0
	global_load_dword v42, v[44:45], off nt
	global_load_dword v43, v[46:47], off nt
	s_nop 0
	global_load_dword v44, v[48:49], off nt
	global_load_dword v45, v[50:51], off nt
	global_load_dword v46, v[52:53], off nt
	global_load_dword v47, v[54:55], off nt
	v_mad_u64_u32 v[48:49], s[4:5], v5, s33, 0
	v_ashrrev_i32_e32 v51, 31, v5
	v_mov_b32_e32 v50, v49
	v_mad_u64_u32 v[50:51], s[4:5], v51, s33, v[50:51]
	v_add_u32_e32 v5, 18, v72
	v_mov_b32_e32 v49, v50
	v_mad_u64_u32 v[50:51], s[4:5], v5, s33, 0
	v_ashrrev_i32_e32 v53, 31, v5
	v_mov_b32_e32 v52, v51
	v_mad_u64_u32 v[52:53], s[4:5], v53, s33, v[52:53]
	v_add_u32_e32 v5, 20, v72
	v_mov_b32_e32 v51, v52
	v_mad_u64_u32 v[52:53], s[4:5], v5, s33, 0
	v_ashrrev_i32_e32 v55, 31, v5
	v_mov_b32_e32 v54, v53
	v_mad_u64_u32 v[54:55], s[4:5], v55, s33, v[54:55]
	v_add_u32_e32 v5, 22, v72
	v_mov_b32_e32 v53, v54
	v_mad_u64_u32 v[54:55], s[4:5], v5, s33, 0
	v_ashrrev_i32_e32 v57, 31, v5
	v_mov_b32_e32 v56, v55
	v_mad_u64_u32 v[56:57], s[4:5], v57, s33, v[56:57]
	v_add_u32_e32 v5, 24, v72
	v_mov_b32_e32 v55, v56
	v_mad_u64_u32 v[56:57], s[4:5], v5, s33, 0
	v_ashrrev_i32_e32 v59, 31, v5
	v_mov_b32_e32 v58, v57
	v_mad_u64_u32 v[58:59], s[4:5], v59, s33, v[58:59]
	v_add_u32_e32 v5, 26, v72
	v_mov_b32_e32 v57, v58
	v_mad_u64_u32 v[58:59], s[4:5], v5, s33, 0
	v_ashrrev_i32_e32 v61, 31, v5
	v_mov_b32_e32 v60, v59
	v_mad_u64_u32 v[60:61], s[4:5], v61, s33, v[60:61]
	v_add_u32_e32 v5, 28, v72
	v_mov_b32_e32 v59, v60
	v_mad_u64_u32 v[60:61], s[4:5], v5, s33, 0
	v_ashrrev_i32_e32 v63, 31, v5
	v_mov_b32_e32 v62, v61
	v_mad_u64_u32 v[62:63], s[4:5], v63, s33, v[62:63]
	v_add_u32_e32 v5, 30, v72
	v_mov_b32_e32 v61, v62
	v_mad_u64_u32 v[62:63], s[4:5], v5, s33, 0
	v_ashrrev_i32_e32 v67, 31, v5
	v_mov_b32_e32 v66, v63
	v_mad_u64_u32 v[66:67], s[4:5], v67, s33, v[66:67]
	v_lshl_add_u64 v[48:49], v[48:49], 2, v[64:65]
	v_lshl_add_u64 v[50:51], v[50:51], 2, v[64:65]
	v_lshl_add_u64 v[52:53], v[52:53], 2, v[64:65]
	v_lshl_add_u64 v[54:55], v[54:55], 2, v[64:65]
	v_lshl_add_u64 v[56:57], v[56:57], 2, v[64:65]
	v_mov_b32_e32 v63, v66
	v_add_u32_e32 v5, 32, v72
	v_lshl_add_u64 v[58:59], v[58:59], 2, v[64:65]
	v_lshl_add_u64 v[60:61], v[60:61], 2, v[64:65]
	v_lshl_add_u64 v[62:63], v[62:63], 2, v[64:65]
	global_load_dword v48, v[48:49], off nt
	s_nop 0
	global_load_dword v49, v[50:51], off nt
	s_nop 0
	global_load_dword v50, v[52:53], off nt
	global_load_dword v51, v[54:55], off nt
	s_nop 0
	global_load_dword v52, v[56:57], off nt
	global_load_dword v53, v[58:59], off nt
	global_load_dword v54, v[60:61], off nt
	global_load_dword v55, v[62:63], off nt
	v_mad_u64_u32 v[56:57], s[4:5], v5, s33, 0
	v_ashrrev_i32_e32 v59, 31, v5
	v_mov_b32_e32 v58, v57
	v_mad_u64_u32 v[58:59], s[4:5], v59, s33, v[58:59]
; __device__ __forceinline__ void p0_load(const TDesc& d, float (&wv)[32], int lane) {
;     const int nblk = d.N / 32, kb = d.item / nblk, nb = d.item % nblk, k0 = 64 * kb, n0 = 32 * nb;
; #pragma unroll
;     for (int i = 0; i < 32; ++i) wv[i] = d.W[(size_t)(k0 + 2 * i + (lane >> 5)) * d.N + n0 + (lane & 31)];
; }
	v_add_u32_e32 v5, 34, v72
	v_mov_b32_e32 v57, v58
	v_mad_u64_u32 v[58:59], s[4:5], v5, s33, 0
	v_ashrrev_i32_e32 v61, 31, v5
	v_mov_b32_e32 v60, v59
	v_mad_u64_u32 v[60:61], s[4:5], v61, s33, v[60:61]
	v_add_u32_e32 v5, 36, v72
	v_mov_b32_e32 v59, v60
	v_mad_u64_u32 v[60:61], s[4:5], v5, s33, 0
	v_ashrrev_i32_e32 v63, 31, v5
	v_mov_b32_e32 v62, v61
	v_mad_u64_u32 v[62:63], s[4:5], v63, s33, v[62:63]
	v_add_u32_e32 v5, 38, v72
	v_mov_b32_e32 v61, v62
	v_mad_u64_u32 v[62:63], s[4:5], v5, s33, 0
	v_ashrrev_i32_e32 v67, 31, v5
	v_mov_b32_e32 v66, v63
	v_mad_u64_u32 v[66:67], s[4:5], v67, s33, v[66:67]
	v_add_u32_e32 v5, 40, v72
	v_mov_b32_e32 v63, v66
	v_mad_u64_u32 v[66:67], s[4:5], v5, s33, 0
	v_ashrrev_i32_e32 v69, 31, v5
	v_mov_b32_e32 v68, v67
	v_mad_u64_u32 v[68:69], s[4:5], v69, s33, v[68:69]
	v_add_u32_e32 v5, 42, v72
	v_mov_b32_e32 v67, v68
	v_mad_u64_u32 v[68:69], s[4:5], v5, s33, 0
	v_ashrrev_i32_e32 v71, 31, v5
	v_mov_b32_e32 v70, v69
	v_mad_u64_u32 v[70:71], s[4:5], v71, s33, v[70:71]
	v_add_u32_e32 v5, 44, v72
	v_mov_b32_e32 v69, v70
	v_mad_u64_u32 v[70:71], s[4:5], v5, s33, 0
	v_ashrrev_i32_e32 v75, 31, v5
	v_mov_b32_e32 v74, v71
	v_mad_u64_u32 v[74:75], s[4:5], v75, s33, v[74:75]
	v_add_u32_e32 v5, 46, v72
	v_mov_b32_e32 v71, v74
	v_mad_u64_u32 v[74:75], s[4:5], v5, s33, 0
	v_ashrrev_i32_e32 v85, 31, v5
	v_mov_b32_e32 v84, v75
	v_mad_u64_u32 v[84:85], s[4:5], v85, s33, v[84:85]
	v_lshl_add_u64 v[56:57], v[56:57], 2, v[64:65]
	v_lshl_add_u64 v[58:59], v[58:59], 2, v[64:65]
	v_lshl_add_u64 v[60:61], v[60:61], 2, v[64:65]
	v_lshl_add_u64 v[62:63], v[62:63], 2, v[64:65]
	v_lshl_add_u64 v[66:67], v[66:67], 2, v[64:65]
	v_mov_b32_e32 v75, v84
	v_add_u32_e32 v5, 48, v72
	v_lshl_add_u64 v[68:69], v[68:69], 2, v[64:65]
	v_lshl_add_u64 v[70:71], v[70:71], 2, v[64:65]
	v_lshl_add_u64 v[74:75], v[74:75], 2, v[64:65]
	global_load_dword v56, v[56:57], off nt
	s_nop 0
	global_load_dword v57, v[58:59], off nt
	s_nop 0
	global_load_dword v58, v[60:61], off nt
	global_load_dword v59, v[62:63], off nt
	s_nop 0
	global_load_dword v60, v[66:67], off nt
	global_load_dword v61, v[68:69], off nt
	global_load_dword v62, v[70:71], off nt
	global_load_dword v63, v[74:75], off nt
	v_mad_u64_u32 v[66:67], s[4:5], v5, s33, 0
	v_ashrrev_i32_e32 v69, 31, v5
	v_mov_b32_e32 v68, v67
	v_mad_u64_u32 v[68:69], s[4:5], v69, s33, v[68:69]
	v_add_u32_e32 v5, 50, v72
	v_mov_b32_e32 v67, v68
	v_mad_u64_u32 v[68:69], s[4:5], v5, s33, 0
	v_ashrrev_i32_e32 v71, 31, v5
	v_mov_b32_e32 v70, v69
	v_mad_u64_u32 v[70:71], s[4:5], v71, s33, v[70:71]
	v_add_u32_e32 v5, 52, v72
	v_mov_b32_e32 v69, v70
	v_mad_u64_u32 v[70:71], s[4:5], v5, s33, 0
	v_ashrrev_i32_e32 v75, 31, v5
	v_mov_b32_e32 v74, v71
	v_mad_u64_u32 v[74:75], s[4:5], v75, s33, v[74:75]
	v_add_u32_e32 v5, 54, v72
	v_mov_b32_e32 v71, v74
	v_mad_u64_u32 v[74:75], s[4:5], v5, s33, 0
	v_ashrrev_i32_e32 v85, 31, v5
	v_mov_b32_e32 v84, v75
	v_mad_u64_u32 v[84:85], s[4:5], v85, s33, v[84:85]
	v_add_u32_e32 v5, 56, v72
	v_mov_b32_e32 v75, v84
	v_mad_u64_u32 v[84:85], s[4:5], v5, s33, 0
	v_ashrrev_i32_e32 v87, 31, v5
	v_mov_b32_e32 v86, v85
	v_mad_u64_u32 v[86:87], s[4:5], v87, s33, v[86:87]
	v_add_u32_e32 v5, 58, v72
	v_mov_b32_e32 v85, v86
	v_mad_u64_u32 v[86:87], s[4:5], v5, s33, 0
	v_ashrrev_i32_e32 v89, 31, v5
	v_mov_b32_e32 v88, v87
	v_mad_u64_u32 v[88:89], s[4:5], v89, s33, v[88:89]
	v_add_u32_e32 v5, 60, v72
	v_mov_b32_e32 v87, v88
	v_mad_u64_u32 v[88:89], s[4:5], v5, s33, 0
	v_ashrrev_i32_e32 v91, 31, v5
	v_mov_b32_e32 v90, v89
	v_mad_u64_u32 v[90:91], s[4:5], v91, s33, v[90:91]
	v_add_u32_e32 v5, 62, v72
	v_mov_b32_e32 v89, v90
	v_mad_u64_u32 v[90:91], s[4:5], v5, s33, 0
	v_ashrrev_i32_e32 v93, 31, v5
	v_mov_b32_e32 v92, v91
	v_mad_u64_u32 v[92:93], s[4:5], v93, s33, v[92:93]
	v_lshl_add_u64 v[66:67], v[66:67], 2, v[64:65]
	v_lshl_add_u64 v[68:69], v[68:69], 2, v[64:65]
	v_lshl_add_u64 v[70:71], v[70:71], 2, v[64:65]
	v_mov_b32_e32 v91, v92
	v_lshl_add_u64 v[74:75], v[74:75], 2, v[64:65]
	v_lshl_add_u64 v[84:85], v[84:85], 2, v[64:65]
	v_lshl_add_u64 v[86:87], v[86:87], 2, v[64:65]
	v_lshl_add_u64 v[88:89], v[88:89], 2, v[64:65]
	v_lshl_add_u64 v[90:91], v[90:91], 2, v[64:65]
	global_load_dword v64, v[66:67], off nt
	global_load_dword v65, v[68:69], off nt
	s_nop 0
	global_load_dword v66, v[70:71], off nt
	global_load_dword v67, v[74:75], off nt
	global_load_dword v68, v[84:85], off nt
	global_load_dword v69, v[86:87], off nt
	s_nop 0
	global_load_dword v70, v[88:89], off nt
	global_load_dword v71, v[90:91], off nt
	s_sext_i32_i16 s33, s30
	v_cvt_f32_i32_e32 v84, s33
	v_cndmask_b32_e64 v5, 0, 1, s[66:67]
	v_cmp_ne_u32_e64 s[4:5], 1, v5
	s_andn2_b64 vcc, exec, s[66:67]
	s_cbranch_vccnz .LBB0_80
; __device__ __forceinline__ void p0_load(const TDesc& d, float (&wv)[32], int lane) {
;     const int nblk = d.N / 32, kb = d.item / nblk, nb = d.item % nblk, k0 = 64 * kb, n0 = 32 * nb;
; #pragma unroll
;     for (int i = 0; i < 32; ++i) wv[i] = d.W[(size_t)(k0 + 2 * i + (lane >> 5)) * d.N + n0 + (lane & 31)];
; }
; __global__ void __launch_bounds__(NWAVES * 64, 2) mega(Args args) {
;     ...
;                 const bool two = it + NGW < DEPTH * NIT;
;                 const TDesc da = mk(it), db = mk(two ? it + NGW : it);
;                 float wa[32], wb[32];
;                 p0_load(da, wa, lane);
;                 if (two) p0_load(db, wb, lane);
	s_lshr_b32 s36, s31, 5
	v_cvt_f32_i32_e32 v8, s36
	s_ashr_i32 s59, s33, 30
	s_or_b32 s59, s59, 1
	v_mov_b32_e32 v5, v3
	v_rcp_iflag_f32_e32 v9, v8
	s_nop 0
	v_mul_f32_e32 v9, v84, v9
	v_trunc_f32_e32 v9, v9
	v_fma_f32 v10, -v9, v8, v84
	v_cvt_i32_f32_e32 v9, v9
	v_cmp_ge_f32_e64 s[66:67], |v10|, v8
	s_and_b64 s[66:67], s[66:67], exec
	s_cselect_b32 s59, s59, 0
	v_readfirstlane_b32 s61, v9
	s_add_i32 s59, s61, s59
	s_sext_i32_i16 s61, s59
	s_mul_i32 s59, s59, s36
	s_sub_i32 s36, s30, s59
	s_sext_i32_i16 s36, s36
	s_lshl_b32 s66, s36, 5
	s_ashr_i32 s67, s66, 31
	s_lshl_b64 s[66:67], s[66:67], 2
	s_add_u32 s66, s68, s66
	v_lshl_add_u32 v85, s61, 6, v76
	s_addc_u32 s67, s69, s67
	v_lshl_add_u64 v[32:33], s[66:67], 0, v[4:5]
	v_mad_u64_u32 v[8:9], s[66:67], v85, s31, 0
	v_ashrrev_i32_e32 v5, 31, v85
	v_mov_b32_e32 v10, v9
	v_mad_u64_u32 v[10:11], s[66:67], v5, s31, v[10:11]
	v_add_u32_e32 v5, 2, v85
	v_mov_b32_e32 v9, v10
	v_mad_u64_u32 v[10:11], s[66:67], v5, s31, 0
	v_ashrrev_i32_e32 v13, 31, v5
	v_mov_b32_e32 v12, v11
	v_mad_u64_u32 v[12:13], s[66:67], v13, s31, v[12:13]
	v_add_u32_e32 v5, 4, v85
	v_mov_b32_e32 v11, v12
	v_mad_u64_u32 v[12:13], s[66:67], v5, s31, 0
	v_ashrrev_i32_e32 v15, 31, v5
	v_mov_b32_e32 v14, v13
	v_mad_u64_u32 v[14:15], s[66:67], v15, s31, v[14:15]
	v_add_u32_e32 v5, 6, v85
	v_mov_b32_e32 v13, v14
	v_mad_u64_u32 v[14:15], s[66:67], v5, s31, 0
	v_ashrrev_i32_e32 v17, 31, v5
	v_mov_b32_e32 v16, v15
	v_mad_u64_u32 v[16:17], s[66:67], v17, s31, v[16:17]
	v_add_u32_e32 v5, 8, v85
	v_mov_b32_e32 v15, v16
	v_mad_u64_u32 v[16:17], s[66:67], v5, s31, 0
	v_ashrrev_i32_e32 v19, 31, v5
	v_mov_b32_e32 v18, v17
	v_mad_u64_u32 v[18:19], s[66:67], v19, s31, v[18:19]
	v_add_u32_e32 v5, 10, v85
	v_mov_b32_e32 v17, v18
	v_mad_u64_u32 v[18:19], s[66:67], v5, s31, 0
	v_ashrrev_i32_e32 v21, 31, v5
	v_mov_b32_e32 v20, v19
	v_mad_u64_u32 v[20:21], s[66:67], v21, s31, v[20:21]
	v_add_u32_e32 v5, 12, v85
	v_mov_b32_e32 v19, v20
	v_mad_u64_u32 v[20:21], s[66:67], v5, s31, 0
	v_ashrrev_i32_e32 v23, 31, v5
	v_mov_b32_e32 v22, v21
	v_mad_u64_u32 v[22:23], s[66:67], v23, s31, v[22:23]
	v_add_u32_e32 v5, 14, v85
	v_mov_b32_e32 v21, v22
	v_mad_u64_u32 v[22:23], s[66:67], v5, s31, 0
	v_ashrrev_i32_e32 v25, 31, v5
	v_mov_b32_e32 v24, v23
	v_mad_u64_u32 v[24:25], s[66:67], v25, s31, v[24:25]
	v_lshl_add_u64 v[8:9], v[8:9], 2, v[32:33]
	v_lshl_add_u64 v[10:11], v[10:11], 2, v[32:33]
	v_lshl_add_u64 v[12:13], v[12:13], 2, v[32:33]
	v_lshl_add_u64 v[14:15], v[14:15], 2, v[32:33]
	v_lshl_add_u64 v[16:17], v[16:17], 2, v[32:33]
	v_mov_b32_e32 v23, v24
	v_add_u32_e32 v5, 16, v85
	v_lshl_add_u64 v[18:19], v[18:19], 2, v[32:33]
	v_lshl_add_u64 v[20:21], v[20:21], 2, v[32:33]
	v_lshl_add_u64 v[22:23], v[22:23], 2, v[32:33]
	global_load_dword v8, v[8:9], off nt
	s_nop 0
	global_load_dword v9, v[10:11], off nt
	s_nop 0
	global_load_dword v10, v[12:13], off nt
	global_load_dword v11, v[14:15], off nt
	s_nop 0
	global_load_dword v12, v[16:17], off nt
	global_load_dword v13, v[18:19], off nt
	global_load_dword v14, v[20:21], off nt
	global_load_dword v15, v[22:23], off nt
	v_mad_u64_u32 v[16:17], s[66:67], v5, s31, 0
	v_ashrrev_i32_e32 v19, 31, v5
	v_mov_b32_e32 v18, v17
	v_mad_u64_u32 v[18:19], s[66:67], v19, s31, v[18:19]
	v_add_u32_e32 v5, 18, v85
	v_mov_b32_e32 v17, v18
	v_mad_u64_u32 v[18:19], s[66:67], v5, s31, 0
	v_ashrrev_i32_e32 v21, 31, v5
	v_mov_b32_e32 v20, v19
	v_mad_u64_u32 v[20:21], s[66:67], v21, s31, v[20:21]
	v_add_u32_e32 v5, 20, v85
	v_mov_b32_e32 v19, v20
	v_mad_u64_u32 v[20:21], s[66:67], v5, s31, 0
	v_ashrrev_i32_e32 v23, 31, v5
	v_mov_b32_e32 v22, v21
	v_mad_u64_u32 v[22:23], s[66:67], v23, s31, v[22:23]
	v_add_u32_e32 v5, 22, v85
	v_mov_b32_e32 v21, v22
	v_mad_u64_u32 v[22:23], s[66:67], v5, s31, 0
	v_ashrrev_i32_e32 v25, 31, v5
	v_mov_b32_e32 v24, v23
	v_mad_u64_u32 v[24:25], s[66:67], v25, s31, v[24:25]
	v_add_u32_e32 v5, 24, v85
	v_mov_b32_e32 v23, v24
	v_mad_u64_u32 v[24:25], s[66:67], v5, s31, 0
	v_ashrrev_i32_e32 v27, 31, v5
	v_mov_b32_e32 v26, v25
	v_mad_u64_u32 v[26:27], s[66:67], v27, s31, v[26:27]
	v_add_u32_e32 v5, 26, v85
	v_mov_b32_e32 v25, v26
	v_mad_u64_u32 v[26:27], s[66:67], v5, s31, 0
	v_ashrrev_i32_e32 v29, 31, v5
	v_mov_b32_e32 v28, v27
	v_mad_u64_u32 v[28:29], s[66:67], v29, s31, v[28:29]
	v_add_u32_e32 v5, 28, v85
	v_mov_b32_e32 v27, v28
	v_mad_u64_u32 v[28:29], s[66:67], v5, s31, 0
	v_ashrrev_i32_e32 v31, 31, v5
	v_mov_b32_e32 v30, v29
	v_mad_u64_u32 v[30:31], s[66:67], v31, s31, v[30:31]
	v_add_u32_e32 v5, 30, v85
	v_mov_b32_e32 v29, v30
	v_mad_u64_u32 v[30:31], s[66:67], v5, s31, 0
	v_ashrrev_i32_e32 v35, 31, v5
	v_mov_b32_e32 v34, v31
	v_mad_u64_u32 v[34:35], s[66:67], v35, s31, v[34:35]
	v_lshl_add_u64 v[16:17], v[16:17], 2, v[32:33]
	v_lshl_add_u64 v[18:19], v[18:19], 2, v[32:33]
	v_lshl_add_u64 v[20:21], v[20:21], 2, v[32:33]
	v_lshl_add_u64 v[22:23], v[22:23], 2, v[32:33]
	v_lshl_add_u64 v[24:25], v[24:25], 2, v[32:33]
	v_mov_b32_e32 v31, v34
	v_add_u32_e32 v5, 32, v85
	v_lshl_add_u64 v[26:27], v[26:27], 2, v[32:33]
	v_lshl_add_u64 v[28:29], v[28:29], 2, v[32:33]
	v_lshl_add_u64 v[30:31], v[30:31], 2, v[32:33]
	global_load_dword v16, v[16:17], off nt
	s_nop 0
	global_load_dword v17, v[18:19], off nt
	s_nop 0
	global_load_dword v18, v[20:21], off nt
	global_load_dword v19, v[22:23], off nt
	s_nop 0
	global_load_dword v20, v[24:25], off nt
	global_load_dword v21, v[26:27], off nt
	global_load_dword v22, v[28:29], off nt
	global_load_dword v23, v[30:31], off nt
	v_mad_u64_u32 v[24:25], s[66:67], v5, s31, 0
	v_ashrrev_i32_e32 v27, 31, v5
	v_mov_b32_e32 v26, v25
	v_mad_u64_u32 v[26:27], s[66:67], v27, s31, v[26:27]
; __device__ __forceinline__ void p0_load(const TDesc& d, float (&wv)[32], int lane) {
;     const int nblk = d.N / 32, kb = d.item / nblk, nb = d.item % nblk, k0 = 64 * kb, n0 = 32 * nb;
; #pragma unroll
;     for (int i = 0; i < 32; ++i) wv[i] = d.W[(size_t)(k0 + 2 * i + (lane >> 5)) * d.N + n0 + (lane & 31)];
; }
	v_add_u32_e32 v5, 34, v85
	v_mov_b32_e32 v25, v26
	v_mad_u64_u32 v[26:27], s[66:67], v5, s31, 0
	v_ashrrev_i32_e32 v29, 31, v5
	v_mov_b32_e32 v28, v27
	v_mad_u64_u32 v[28:29], s[66:67], v29, s31, v[28:29]
	v_add_u32_e32 v5, 36, v85
	v_mov_b32_e32 v27, v28
	v_mad_u64_u32 v[28:29], s[66:67], v5, s31, 0
	v_ashrrev_i32_e32 v31, 31, v5
	v_mov_b32_e32 v30, v29
	v_mad_u64_u32 v[30:31], s[66:67], v31, s31, v[30:31]
	v_add_u32_e32 v5, 38, v85
	v_mov_b32_e32 v29, v30
	v_mad_u64_u32 v[30:31], s[66:67], v5, s31, 0
	v_ashrrev_i32_e32 v35, 31, v5
	v_mov_b32_e32 v34, v31
	v_mad_u64_u32 v[34:35], s[66:67], v35, s31, v[34:35]
	v_add_u32_e32 v5, 40, v85
	v_mov_b32_e32 v31, v34
	v_mad_u64_u32 v[34:35], s[66:67], v5, s31, 0
	v_ashrrev_i32_e32 v37, 31, v5
	v_mov_b32_e32 v36, v35
	v_mad_u64_u32 v[36:37], s[66:67], v37, s31, v[36:37]
	v_add_u32_e32 v5, 42, v85
	v_mov_b32_e32 v35, v36
	v_mad_u64_u32 v[36:37], s[66:67], v5, s31, 0
	v_ashrrev_i32_e32 v39, 31, v5
	v_mov_b32_e32 v38, v37
	v_mad_u64_u32 v[38:39], s[66:67], v39, s31, v[38:39]
	v_add_u32_e32 v5, 44, v85
	v_mov_b32_e32 v37, v38
	v_mad_u64_u32 v[38:39], s[66:67], v5, s31, 0
	v_ashrrev_i32_e32 v75, 31, v5
	v_mov_b32_e32 v74, v39
	v_mad_u64_u32 v[74:75], s[66:67], v75, s31, v[74:75]
	v_add_u32_e32 v5, 46, v85
	v_mov_b32_e32 v39, v74
	v_mad_u64_u32 v[74:75], s[66:67], v5, s31, 0
	v_ashrrev_i32_e32 v87, 31, v5
	v_mov_b32_e32 v86, v75
	v_mad_u64_u32 v[86:87], s[66:67], v87, s31, v[86:87]
	v_lshl_add_u64 v[24:25], v[24:25], 2, v[32:33]
	v_lshl_add_u64 v[26:27], v[26:27], 2, v[32:33]
	v_lshl_add_u64 v[28:29], v[28:29], 2, v[32:33]
	v_lshl_add_u64 v[30:31], v[30:31], 2, v[32:33]
	v_lshl_add_u64 v[34:35], v[34:35], 2, v[32:33]
	v_mov_b32_e32 v75, v86
	v_add_u32_e32 v5, 48, v85
	v_lshl_add_u64 v[36:37], v[36:37], 2, v[32:33]
	v_lshl_add_u64 v[38:39], v[38:39], 2, v[32:33]
	v_lshl_add_u64 v[74:75], v[74:75], 2, v[32:33]
	global_load_dword v24, v[24:25], off nt
	s_nop 0
	global_load_dword v25, v[26:27], off nt
	s_nop 0
	global_load_dword v26, v[28:29], off nt
	global_load_dword v27, v[30:31], off nt
	s_nop 0
	global_load_dword v28, v[34:35], off nt
	global_load_dword v29, v[36:37], off nt
	global_load_dword v30, v[38:39], off nt
	global_load_dword v31, v[74:75], off nt
	v_mad_u64_u32 v[34:35], s[66:67], v5, s31, 0
	v_ashrrev_i32_e32 v37, 31, v5
	v_mov_b32_e32 v36, v35
	v_mad_u64_u32 v[36:37], s[66:67], v37, s31, v[36:37]
	v_add_u32_e32 v5, 50, v85
	v_mov_b32_e32 v35, v36
	v_mad_u64_u32 v[36:37], s[66:67], v5, s31, 0
	v_ashrrev_i32_e32 v39, 31, v5
	v_mov_b32_e32 v38, v37
	v_mad_u64_u32 v[38:39], s[66:67], v39, s31, v[38:39]
	v_add_u32_e32 v5, 52, v85
	v_mov_b32_e32 v37, v38
	v_mad_u64_u32 v[38:39], s[66:67], v5, s31, 0
	v_ashrrev_i32_e32 v75, 31, v5
	v_mov_b32_e32 v74, v39
	v_mad_u64_u32 v[74:75], s[66:67], v75, s31, v[74:75]
	v_add_u32_e32 v5, 54, v85
	v_mov_b32_e32 v39, v74
	v_mad_u64_u32 v[74:75], s[66:67], v5, s31, 0
	v_ashrrev_i32_e32 v87, 31, v5
	v_mov_b32_e32 v86, v75
	v_mad_u64_u32 v[86:87], s[66:67], v87, s31, v[86:87]
	v_add_u32_e32 v5, 56, v85
	v_mov_b32_e32 v75, v86
	v_mad_u64_u32 v[86:87], s[66:67], v5, s31, 0
	v_ashrrev_i32_e32 v89, 31, v5
	v_mov_b32_e32 v88, v87
	v_mad_u64_u32 v[88:89], s[66:67], v89, s31, v[88:89]
	v_add_u32_e32 v5, 58, v85
	v_mov_b32_e32 v87, v88
	v_mad_u64_u32 v[88:89], s[66:67], v5, s31, 0
	v_ashrrev_i32_e32 v91, 31, v5
	v_mov_b32_e32 v90, v89
	v_mad_u64_u32 v[90:91], s[66:67], v91, s31, v[90:91]
	v_add_u32_e32 v5, 60, v85
	v_mov_b32_e32 v89, v90
	v_mad_u64_u32 v[90:91], s[66:67], v5, s31, 0
	v_ashrrev_i32_e32 v93, 31, v5
	v_mov_b32_e32 v92, v91
	v_mad_u64_u32 v[92:93], s[66:67], v93, s31, v[92:93]
	v_add_u32_e32 v5, 62, v85
	v_mov_b32_e32 v91, v92
	v_mad_u64_u32 v[92:93], s[66:67], v5, s31, 0
	v_ashrrev_i32_e32 v85, 31, v5
	v_mov_b32_e32 v94, v93
	v_mad_u64_u32 v[94:95], s[66:67], v85, s31, v[94:95]
	v_lshl_add_u64 v[34:35], v[34:35], 2, v[32:33]
	v_lshl_add_u64 v[36:37], v[36:37], 2, v[32:33]
	v_lshl_add_u64 v[38:39], v[38:39], 2, v[32:33]
	v_mov_b32_e32 v93, v94
	v_lshl_add_u64 v[74:75], v[74:75], 2, v[32:33]
	v_lshl_add_u64 v[86:87], v[86:87], 2, v[32:33]
	v_lshl_add_u64 v[88:89], v[88:89], 2, v[32:33]
	v_lshl_add_u64 v[90:91], v[90:91], 2, v[32:33]
	v_lshl_add_u64 v[92:93], v[92:93], 2, v[32:33]
	global_load_dword v32, v[34:35], off nt
	global_load_dword v33, v[36:37], off nt
	s_nop 0
	global_load_dword v34, v[38:39], off nt
	global_load_dword v35, v[74:75], off nt
	global_load_dword v36, v[86:87], off nt
	global_load_dword v37, v[88:89], off nt
	s_nop 0
	global_load_dword v38, v[90:91], off nt
	global_load_dword v39, v[92:93], off nt
; __device__ __forceinline__ unsigned f2bf(float f) { unsigned u = __builtin_bit_cast(unsigned, f); return (u + 0x7fffu + ((u >> 16) & 1u)) >> 16; }
; __device__ __forceinline__ void p0_finish(const TDesc& d, float (&wv)[32], LAS float* scr, int lane) {
;     ...
;     if (d.gsc) {
;         float c1 = 0.f, c2 = 0.f;
; #pragma unroll
;         for (int i = 0; i < 32; ++i) { const int k = k0 + 2 * i + (lane >> 5); c2 += d.bsc[k] * wv[i]; wv[i] *= d.gsc[k]; c1 += bf2f((unsigned short)f2bf(wv[i])); }
;         c1 += __shfl_xor(c1, 32); c2 += __shfl_xor(c2, 32);
;         if (lane < 32) { float* p = d.cvp + (size_t)kb * 2 * 4096 + n0 + lane; p[0] = c1; p[4096] = c2; }
.LBB0_80:
	s_cmp_eq_u64 s[54:55], 0
	s_cbranch_scc1 .LBB0_84
	v_lshlrev_b64 v[72:73], 2, v[72:73]
	v_lshl_add_u64 v[74:75], s[56:57], 0, v[72:73]
	v_lshl_add_u64 v[72:73], s[54:55], 0, v[72:73]
	global_load_dword v5, v[74:75], off nt
	global_load_dword v85, v[74:75], off offset:8 nt
	global_load_dword v86, v[72:73], off nt
	global_load_dword v87, v[72:73], off offset:8 nt
	global_load_dword v106, v[74:75], off offset:16 nt
	global_load_dword v107, v[74:75], off offset:24 nt
	global_load_dword v88, v[72:73], off offset:16 nt
	global_load_dword v89, v[72:73], off offset:24 nt
	global_load_dword v108, v[74:75], off offset:32 nt
	global_load_dword v109, v[74:75], off offset:40 nt
	global_load_dword v90, v[72:73], off offset:32 nt
	global_load_dword v91, v[72:73], off offset:40 nt
	global_load_dword v110, v[74:75], off offset:48 nt
	global_load_dword v111, v[74:75], off offset:56 nt
	global_load_dword v92, v[72:73], off offset:48 nt
	global_load_dword v93, v[72:73], off offset:56 nt
	global_load_dword v112, v[74:75], off offset:64 nt
	global_load_dword v113, v[74:75], off offset:72 nt
	global_load_dword v94, v[72:73], off offset:64 nt
	global_load_dword v95, v[72:73], off offset:72 nt
	global_load_dword v114, v[74:75], off offset:80 nt
	global_load_dword v115, v[74:75], off offset:88 nt
	global_load_dword v96, v[72:73], off offset:80 nt
	global_load_dword v97, v[72:73], off offset:88 nt
	global_load_dword v116, v[74:75], off offset:96 nt
	global_load_dword v117, v[74:75], off offset:104 nt
	global_load_dword v118, v[74:75], off offset:112 nt
	global_load_dword v119, v[74:75], off offset:120 nt
	global_load_dword v98, v[72:73], off offset:96 nt
	global_load_dword v99, v[72:73], off offset:104 nt
	global_load_dword v100, v[72:73], off offset:112 nt
	global_load_dword v101, v[72:73], off offset:120 nt
	global_load_dword v120, v[74:75], off offset:128 nt
	global_load_dword v121, v[74:75], off offset:136 nt
	global_load_dword v122, v[74:75], off offset:144 nt
	global_load_dword v123, v[74:75], off offset:152 nt
	global_load_dword v102, v[72:73], off offset:128 nt
	global_load_dword v103, v[72:73], off offset:136 nt
	global_load_dword v104, v[72:73], off offset:144 nt
	global_load_dword v105, v[72:73], off offset:152 nt
	s_waitcnt vmcnt(39)
	v_fma_f32 v5, v40, v5, 0
	s_waitcnt vmcnt(38)
	v_fmac_f32_e32 v5, v41, v85
	s_waitcnt vmcnt(36)
	v_pk_mul_f32 v[40:41], v[40:41], v[86:87]
	s_nop 0
	v_bfe_u32 v85, v40, 16, 1
	s_waitcnt vmcnt(35)
	v_fmac_f32_e32 v5, v42, v106
	v_bfe_u32 v86, v41, 16, 1
	v_add3_u32 v85, v40, v85, s28
	s_waitcnt vmcnt(34)
	v_fmac_f32_e32 v5, v43, v107
	s_waitcnt vmcnt(32)
	v_pk_mul_f32 v[42:43], v[42:43], v[88:89]
	v_add3_u32 v86, v41, v86, s28
	v_and_b32_e32 v85, 0xffff0000, v85
	v_bfe_u32 v87, v42, 16, 1
	v_bfe_u32 v88, v43, 16, 1
	s_waitcnt vmcnt(31)
	v_fmac_f32_e32 v5, v44, v108
	v_and_b32_e32 v86, 0xffff0000, v86
	v_add_f32_e32 v85, 0, v85
	v_add3_u32 v87, v42, v87, s28
	v_add3_u32 v88, v43, v88, s28
	s_waitcnt vmcnt(30)
	v_fmac_f32_e32 v5, v45, v109
	s_waitcnt vmcnt(28)
	v_pk_mul_f32 v[44:45], v[44:45], v[90:91]
	v_add_f32_e32 v85, v85, v86
	v_and_b32_e32 v86, 0xffff0000, v87
	v_and_b32_e32 v87, 0xffff0000, v88
	v_bfe_u32 v88, v44, 16, 1
	v_bfe_u32 v89, v45, 16, 1
	s_waitcnt vmcnt(27)
	v_fmac_f32_e32 v5, v46, v110
	v_add_f32_e32 v85, v85, v86
	v_add3_u32 v86, v44, v88, s28
	v_add3_u32 v88, v45, v89, s28
	s_waitcnt vmcnt(26)
	v_fmac_f32_e32 v5, v47, v111
	s_waitcnt vmcnt(24)
	v_pk_mul_f32 v[46:47], v[46:47], v[92:93]
	v_add_f32_e32 v85, v85, v87
	v_and_b32_e32 v86, 0xffff0000, v86
	v_and_b32_e32 v87, 0xffff0000, v88
	v_bfe_u32 v88, v46, 16, 1
	v_bfe_u32 v89, v47, 16, 1
	s_waitcnt vmcnt(23)
	v_fmac_f32_e32 v5, v48, v112
	v_add_f32_e32 v85, v85, v86
	v_add3_u32 v86, v46, v88, s28
	v_add3_u32 v88, v47, v89, s28
	s_waitcnt vmcnt(22)
	v_fmac_f32_e32 v5, v49, v113
	s_waitcnt vmcnt(20)
	v_pk_mul_f32 v[48:49], v[48:49], v[94:95]
	v_add_f32_e32 v85, v85, v87
	v_and_b32_e32 v86, 0xffff0000, v86
	v_and_b32_e32 v87, 0xffff0000, v88
	v_bfe_u32 v88, v48, 16, 1
	v_add_f32_e32 v85, v85, v86
	v_add3_u32 v86, v48, v88, s28
	v_add_f32_e32 v85, v85, v87
	v_and_b32_e32 v86, 0xffff0000, v86
	v_add_f32_e32 v85, v85, v86
	global_load_dword v106, v[74:75], off offset:160 nt
	global_load_dword v107, v[74:75], off offset:168 nt
	global_load_dword v86, v[72:73], off offset:160 nt
	global_load_dword v87, v[72:73], off offset:168 nt
	v_bfe_u32 v89, v49, 16, 1
	v_add3_u32 v88, v49, v89, s28
	s_waitcnt vmcnt(23)
	v_fmac_f32_e32 v5, v50, v114
	v_and_b32_e32 v88, 0xffff0000, v88
	s_waitcnt vmcnt(22)
	v_fmac_f32_e32 v5, v51, v115
	s_waitcnt vmcnt(20)
	v_pk_mul_f32 v[50:51], v[50:51], v[96:97]
	v_add_f32_e32 v85, v85, v88
	v_bfe_u32 v88, v50, 16, 1
	v_add3_u32 v90, v50, v88, s28
	global_load_dword v96, v[74:75], off offset:176 nt
	global_load_dword v97, v[74:75], off offset:184 nt
	global_load_dword v88, v[72:73], off offset:176 nt
	global_load_dword v89, v[72:73], off offset:184 nt
	v_and_b32_e32 v90, 0xffff0000, v90
	v_add_f32_e32 v85, v85, v90
	v_bfe_u32 v90, v51, 16, 1
	v_add3_u32 v90, v51, v90, s28
	v_and_b32_e32 v90, 0xffff0000, v90
	v_add_f32_e32 v85, v85, v90
	global_load_dword v108, v[74:75], off offset:192 nt
	global_load_dword v109, v[74:75], off offset:200 nt
	global_load_dword v90, v[72:73], off offset:192 nt
	global_load_dword v91, v[72:73], off offset:200 nt
	s_waitcnt vmcnt(27)
	v_fmac_f32_e32 v5, v52, v116
	s_waitcnt vmcnt(26)
; __device__ __forceinline__ unsigned f2bf(float f) { unsigned u = __builtin_bit_cast(unsigned, f); return (u + 0x7fffu + ((u >> 16) & 1u)) >> 16; }
; __device__ __forceinline__ void p0_finish(const TDesc& d, float (&wv)[32], LAS float* scr, int lane) {
;     ...
;         for (int i = 0; i < 32; ++i) { const int k = k0 + 2 * i + (lane >> 5); c2 += d.bsc[k] * wv[i]; wv[i] *= d.gsc[k]; c1 += bf2f((unsigned short)f2bf(wv[i])); }
;         c1 += __shfl_xor(c1, 32); c2 += __shfl_xor(c2, 32);
;         if (lane < 32) { float* p = d.cvp + (size_t)kb * 2 * 4096 + n0 + lane; p[0] = c1; p[4096] = c2; }
;     }
	v_fmac_f32_e32 v5, v53, v117
	s_waitcnt vmcnt(22)
	v_pk_mul_f32 v[52:53], v[52:53], v[98:99]
	v_fmac_f32_e32 v5, v54, v118
	v_bfe_u32 v92, v52, 16, 1
	v_add3_u32 v92, v52, v92, s28
	v_and_b32_e32 v92, 0xffff0000, v92
	v_add_f32_e32 v85, v85, v92
	global_load_dword v98, v[74:75], off offset:208 nt
	global_load_dword v99, v[74:75], off offset:216 nt
	global_load_dword v92, v[72:73], off offset:208 nt
	global_load_dword v93, v[72:73], off offset:216 nt
	v_bfe_u32 v94, v53, 16, 1
	v_add3_u32 v94, v53, v94, s28
	v_and_b32_e32 v94, 0xffff0000, v94
	v_fmac_f32_e32 v5, v55, v119
	s_waitcnt vmcnt(24)
	v_pk_mul_f32 v[54:55], v[54:55], v[100:101]
	v_add_f32_e32 v85, v85, v94
	v_bfe_u32 v100, v54, 16, 1
	global_load_dword v101, v[74:75], off offset:224 nt
	global_load_dword v110, v[74:75], off offset:232 nt
	global_load_dword v94, v[72:73], off offset:224 nt
	global_load_dword v95, v[72:73], off offset:232 nt
	v_add3_u32 v100, v54, v100, s28
	v_and_b32_e32 v100, 0xffff0000, v100
	v_add_f32_e32 v85, v85, v100
	v_bfe_u32 v100, v55, 16, 1
	v_add3_u32 v100, v55, v100, s28
	v_and_b32_e32 v100, 0xffff0000, v100
	v_add_f32_e32 v85, v85, v100
	global_load_dword v100, v[74:75], off offset:240 nt
	global_load_dword v111, v[74:75], off offset:248 nt
	s_nop 0
	global_load_dword v74, v[72:73], off offset:240 nt
	global_load_dword v75, v[72:73], off offset:248 nt
	s_waitcnt vmcnt(31)
	v_fmac_f32_e32 v5, v56, v120
	s_waitcnt vmcnt(30)
	v_fmac_f32_e32 v5, v57, v121
	s_waitcnt vmcnt(26)
	v_pk_mul_f32 v[56:57], v[56:57], v[102:103]
	v_fmac_f32_e32 v5, v58, v122
	v_bfe_u32 v72, v56, 16, 1
	v_add3_u32 v72, v56, v72, s28
	v_bfe_u32 v73, v57, 16, 1
	v_and_b32_e32 v72, 0xffff0000, v72
	v_add3_u32 v73, v57, v73, s28
	v_add_f32_e32 v72, v85, v72
	v_and_b32_e32 v73, 0xffff0000, v73
	v_fmac_f32_e32 v5, v59, v123
	s_waitcnt vmcnt(24)
	v_pk_mul_f32 v[58:59], v[58:59], v[104:105]
	v_add_f32_e32 v72, v72, v73
	v_bfe_u32 v73, v58, 16, 1
	v_add3_u32 v73, v58, v73, s28
	v_and_b32_e32 v73, 0xffff0000, v73
	v_add_f32_e32 v72, v72, v73
	v_bfe_u32 v73, v59, 16, 1
	v_add3_u32 v73, v59, v73, s28
	v_and_b32_e32 v73, 0xffff0000, v73
	v_add_f32_e32 v72, v72, v73
	s_waitcnt vmcnt(23)
	v_fmac_f32_e32 v5, v60, v106
	s_waitcnt vmcnt(22)
	v_fmac_f32_e32 v5, v61, v107
	s_waitcnt vmcnt(20)
	v_pk_mul_f32 v[60:61], v[60:61], v[86:87]
	s_nop 0
	v_bfe_u32 v73, v60, 16, 1
	v_add3_u32 v73, v60, v73, s28
	v_and_b32_e32 v73, 0xffff0000, v73
	v_add_f32_e32 v72, v72, v73
	v_bfe_u32 v73, v61, 16, 1
	v_add3_u32 v73, v61, v73, s28
	s_waitcnt vmcnt(19)
	v_fmac_f32_e32 v5, v62, v96
	v_and_b32_e32 v73, 0xffff0000, v73
	s_waitcnt vmcnt(18)
	v_fmac_f32_e32 v5, v63, v97
	s_waitcnt vmcnt(16)
	v_pk_mul_f32 v[62:63], v[62:63], v[88:89]
	v_add_f32_e32 v72, v72, v73
	v_bfe_u32 v73, v62, 16, 1
	v_add3_u32 v73, v62, v73, s28
	v_and_b32_e32 v73, 0xffff0000, v73
	v_add_f32_e32 v72, v72, v73
	v_bfe_u32 v73, v63, 16, 1
	v_add3_u32 v73, v63, v73, s28
	s_waitcnt vmcnt(15)
	v_fmac_f32_e32 v5, v64, v108
	v_and_b32_e32 v73, 0xffff0000, v73
	s_waitcnt vmcnt(14)
	v_fmac_f32_e32 v5, v65, v109
	s_waitcnt vmcnt(12)
	v_pk_mul_f32 v[64:65], v[64:65], v[90:91]
	v_add_f32_e32 v72, v72, v73
	v_bfe_u32 v73, v64, 16, 1
	v_add3_u32 v73, v64, v73, s28
	v_and_b32_e32 v73, 0xffff0000, v73
	v_add_f32_e32 v72, v72, v73
	v_bfe_u32 v73, v65, 16, 1
	v_add3_u32 v73, v65, v73, s28
	s_waitcnt vmcnt(11)
	v_fmac_f32_e32 v5, v66, v98
	v_and_b32_e32 v73, 0xffff0000, v73
	s_waitcnt vmcnt(10)
	v_fmac_f32_e32 v5, v67, v99
	s_waitcnt vmcnt(8)
	v_pk_mul_f32 v[66:67], v[66:67], v[92:93]
	v_add_f32_e32 v72, v72, v73
	v_bfe_u32 v73, v66, 16, 1
	v_add3_u32 v73, v66, v73, s28
	v_and_b32_e32 v73, 0xffff0000, v73
	v_add_f32_e32 v72, v72, v73
	v_bfe_u32 v73, v67, 16, 1
	v_add3_u32 v73, v67, v73, s28
	s_waitcnt vmcnt(7)
	v_fmac_f32_e32 v5, v68, v101
	v_and_b32_e32 v73, 0xffff0000, v73
	s_waitcnt vmcnt(6)
	v_fmac_f32_e32 v5, v69, v110
	s_waitcnt vmcnt(4)
	v_pk_mul_f32 v[68:69], v[68:69], v[94:95]
	v_add_f32_e32 v72, v72, v73
	v_bfe_u32 v73, v68, 16, 1
	v_add3_u32 v73, v68, v73, s28
	v_and_b32_e32 v73, 0xffff0000, v73
	v_add_f32_e32 v72, v72, v73
	v_bfe_u32 v73, v69, 16, 1
	v_add3_u32 v73, v69, v73, s28
	s_waitcnt vmcnt(3)
	v_fmac_f32_e32 v5, v70, v100
	v_and_b32_e32 v73, 0xffff0000, v73
	s_waitcnt vmcnt(2)
	v_fmac_f32_e32 v5, v71, v111
	s_waitcnt vmcnt(0)
	v_pk_mul_f32 v[70:71], v[70:71], v[74:75]
	v_add_f32_e32 v72, v72, v73
	v_bfe_u32 v73, v70, 16, 1
	v_add3_u32 v73, v70, v73, s28
	v_and_b32_e32 v73, 0xffff0000, v73
	v_add_f32_e32 v72, v72, v73
	v_bfe_u32 v73, v71, 16, 1
	v_add3_u32 v73, v71, v73, s28
	v_and_b32_e32 v73, 0xffff0000, v73
	v_and_b32_e32 v74, 64, v83
	v_add_f32_e32 v72, v72, v73
	v_xor_b32_e32 v73, 32, v83
	v_add_u32_e32 v74, 64, v74
	v_cmp_lt_i32_e32 vcc, v73, v74
	s_nop 1
	v_cndmask_b32_e32 v73, v83, v73, vcc
	v_lshlrev_b32_e32 v74, 2, v73
	ds_bpermute_b32 v73, v74, v72
	ds_bpermute_b32 v74, v74, v5
	s_and_saveexec_b64 s[54:55], s[0:1]
	s_cbranch_execz .LBB0_83
	s_ashr_i32 s63, s62, 31
	s_lshl_b64 s[56:57], s[62:63], 15
	s_add_u32 s36, s48, s56
	s_addc_u32 s49, s49, s57
	s_add_u32 s48, s36, s64
	s_addc_u32 s49, s49, s65
	s_waitcnt lgkmcnt(0)
	v_add_f32_e32 v5, v5, v74
	v_add_f32_e32 v74, v72, v73
	v_lshl_add_u64 v[72:73], v[0:1], 2, s[48:49]
	global_store_dword v[72:73], v74, off
	v_add_co_u32_e32 v72, vcc, 0x4000, v72
	s_nop 1
	v_addc_co_u32_e32 v73, vcc, 0, v73, vcc
	global_store_dword v[72:73], v5, off

; #define LAS __attribute__((address_space(3)))
; __device__ __forceinline__ unsigned pk2(float lo, float hi) { const f32x2_t v = {lo, hi}; const bf16x2_t b = __builtin_convertvector(v, bf16x2_t); return __builtin_bit_cast(unsigned, b); }
; #define LDS_WAIT() asm volatile("s_waitcnt lgkmcnt(0)" ::: "memory")
; __device__ __forceinline__ void p0_finish(const TDesc& d, float (&wv)[32], LAS float* scr, int lane) {
;     ...
; #pragma unroll
;     for (int i = 0; i < 32; ++i) scr[(2 * i + (lane >> 5)) * 33 + (lane & 31)] = wv[i];
;     LDS_WAIT(); asm volatile("" ::: "memory");
;     const int c = lane & 7;
; #pragma unroll
;     for (int j = 0; j < 4; ++j) { const int n = (lane >> 3) + 8 * j; const LAS float* sp = scr + (8 * c) * 33 + n;
;         u32x4 o; o.x = pk2(sp[0 * 33], sp[1 * 33]); o.y = pk2(sp[2 * 33], sp[3 * 33]); o.z = pk2(sp[4 * 33], sp[5 * 33]); o.w = pk2(sp[6 * 33], sp[7 * 33]);
;         *(u32x4*)(d.WT + (size_t)(n0 + n) * K + k0 + 8 * c) = o; }
;     LDS_WAIT(); asm volatile("" ::: "memory");
.LBB0_84:
	v_add_u32_e32 v5, 0x400, v77
	s_waitcnt vmcnt(30)
	ds_write2_b32 v77, v40, v41 offset1:66
	s_waitcnt vmcnt(28)
	ds_write2_b32 v77, v42, v43 offset0:132 offset1:198
	s_waitcnt vmcnt(26)
	ds_write2_b32 v5, v44, v45 offset0:8 offset1:74
	s_waitcnt vmcnt(24)
	ds_write2_b32 v5, v46, v47 offset0:140 offset1:206
	v_add_u32_e32 v5, 0x800, v77
	s_waitcnt vmcnt(22)
	ds_write2_b32 v5, v48, v49 offset0:16 offset1:82
	s_waitcnt vmcnt(20)
	ds_write2_b32 v5, v50, v51 offset0:148 offset1:214
	v_add_u32_e32 v5, 0xc00, v77
	s_waitcnt vmcnt(18)
	ds_write2_b32 v5, v52, v53 offset0:24 offset1:90
	s_waitcnt vmcnt(16)
	ds_write2_b32 v5, v54, v55 offset0:156 offset1:222
	v_add_u32_e32 v5, 0x1000, v77
	s_waitcnt vmcnt(14)
	ds_write2_b32 v5, v56, v57 offset0:32 offset1:98
	s_waitcnt vmcnt(12)
	ds_write2_b32 v5, v58, v59 offset0:164 offset1:230
	v_add_u32_e32 v5, 0x1400, v77
	s_waitcnt vmcnt(10)
	ds_write2_b32 v5, v60, v61 offset0:40 offset1:106
	s_waitcnt vmcnt(8)
	ds_write2_b32 v5, v62, v63 offset0:172 offset1:238
	v_add_u32_e32 v5, 0x1800, v77
	s_waitcnt vmcnt(6)
	ds_write2_b32 v5, v64, v65 offset0:48 offset1:114
	s_waitcnt vmcnt(4)
	ds_write2_b32 v5, v66, v67 offset0:180 offset1:246
	v_add_u32_e32 v5, 0x1c00, v77
	s_waitcnt vmcnt(2)
	ds_write2_b32 v5, v68, v69 offset0:56 offset1:122
	s_waitcnt vmcnt(0)
	ds_write2_b32 v5, v70, v71 offset0:188 offset1:254
	s_waitcnt lgkmcnt(0)
	ds_read2_b32 v[44:45], v79 offset0:33 offset1:41
	ds_read2_b32 v[46:47], v79 offset1:8
	ds_read2_b32 v[48:49], v79 offset0:66 offset1:74
	ds_read2_b32 v[50:51], v79 offset0:99 offset1:107
	ds_read2_b32 v[52:53], v79 offset0:132 offset1:140
	ds_read2_b32 v[54:55], v79 offset0:165 offset1:173
	ds_read2_b32 v[56:57], v79 offset0:198 offset1:206
	ds_read2_b32 v[58:59], v79 offset0:231 offset1:239
	v_add_u32_e32 v5, s58, v78
	s_waitcnt lgkmcnt(0)
	v_cvt_pk_bf16_f32 v40, v46, v44
	v_ashrrev_i32_e32 v44, 31, v5
	v_mul_lo_u32 v44, s44, v44
	v_mul_lo_u32 v46, s45, v5
	v_mad_u64_u32 v[60:61], s[48:49], s44, v5, 0
	s_ashr_i32 s61, s60, 31
	v_add3_u32 v61, v61, v44, v46
	v_lshl_add_u64 v[60:61], v[60:61], 1, s[42:43]
	s_lshl_b64 s[48:49], s[60:61], 1
	v_lshl_add_u64 v[60:61], v[60:61], 0, s[48:49]
	v_add_u32_e32 v5, s58, v80
	v_cvt_pk_bf16_f32 v41, v48, v50
	v_cvt_pk_bf16_f32 v42, v52, v54
	v_cvt_pk_bf16_f32 v43, v56, v58
	v_lshl_add_u64 v[60:61], v[60:61], 0, v[2:3]
	v_ashrrev_i32_e32 v44, 31, v5
	global_store_dwordx4 v[60:61], v[40:43], off sc1
	v_mul_lo_u32 v46, s44, v44
	s_and_b64 vcc, exec, s[4:5]
	v_cvt_pk_bf16_f32 v40, v47, v45
	v_mul_lo_u32 v47, s45, v5
	v_mad_u64_u32 v[44:45], s[54:55], s44, v5, 0
	v_add3_u32 v45, v45, v46, v47
	v_lshl_add_u64 v[44:45], v[44:45], 1, s[42:43]
	v_lshl_add_u64 v[44:45], v[44:45], 0, s[48:49]
	v_cvt_pk_bf16_f32 v41, v49, v51
	v_cvt_pk_bf16_f32 v42, v53, v55
	v_cvt_pk_bf16_f32 v43, v57, v59
	v_lshl_add_u64 v[44:45], v[44:45], 0, v[2:3]
	v_add_u32_e32 v5, s58, v81
	ds_read2_b32 v[46:47], v79 offset0:16 offset1:24
	ds_read2_b32 v[48:49], v79 offset0:49 offset1:57
	ds_read2_b32 v[50:51], v79 offset0:82 offset1:90
	ds_read2_b32 v[52:53], v79 offset0:115 offset1:123
	ds_read2_b32 v[54:55], v79 offset0:148 offset1:156
	ds_read2_b32 v[56:57], v79 offset0:181 offset1:189
	ds_read2_b32 v[58:59], v79 offset0:214 offset1:222
	ds_read2_b32 v[60:61], v79 offset0:247 offset1:255
	global_store_dwordx4 v[44:45], v[40:43], off sc1
	v_ashrrev_i32_e32 v44, 31, v5
	s_waitcnt lgkmcnt(6)
	v_cvt_pk_bf16_f32 v40, v46, v48
	v_mul_lo_u32 v46, s44, v44
	v_mul_lo_u32 v48, s45, v5
	v_mad_u64_u32 v[44:45], s[54:55], s44, v5, 0
	v_add3_u32 v45, v45, v46, v48
	v_lshl_add_u64 v[44:45], v[44:45], 1, s[42:43]
	v_lshl_add_u64 v[44:45], v[44:45], 0, s[48:49]
	s_waitcnt lgkmcnt(4)
	v_cvt_pk_bf16_f32 v41, v50, v52
	s_waitcnt lgkmcnt(2)
	v_cvt_pk_bf16_f32 v42, v54, v56
	s_waitcnt lgkmcnt(0)
	v_cvt_pk_bf16_f32 v43, v58, v60
	v_lshl_add_u64 v[44:45], v[44:45], 0, v[2:3]
	v_add_u32_e32 v5, s58, v82
	global_store_dwordx4 v[44:45], v[40:43], off sc1
	v_ashrrev_i32_e32 v44, 31, v5
	v_mul_lo_u32 v46, s44, v44
	v_cvt_pk_bf16_f32 v40, v47, v49
	v_mul_lo_u32 v47, s45, v5
	v_mad_u64_u32 v[44:45], s[44:45], s44, v5, 0
	v_add3_u32 v45, v45, v46, v47
	v_lshl_add_u64 v[44:45], v[44:45], 1, s[42:43]
	v_lshl_add_u64 v[44:45], v[44:45], 0, s[48:49]
	v_cvt_pk_bf16_f32 v41, v51, v53
	v_cvt_pk_bf16_f32 v42, v55, v57
	v_cvt_pk_bf16_f32 v43, v59, v61
	v_lshl_add_u64 v[44:45], v[44:45], 0, v[2:3]
	global_store_dwordx4 v[44:45], v[40:43], off sc1
	s_waitcnt lgkmcnt(0)
	s_cbranch_vccnz .LBB0_27
	s_lshr_b32 s31, s31, 5
	v_cvt_f32_i32_e32 v5, s31
	s_ashr_i32 s4, s33, 30
	s_or_b32 s33, s4, 1
	v_rcp_iflag_f32_e32 v40, v5
	s_nop 0
	v_mul_f32_e32 v40, v84, v40
	v_trunc_f32_e32 v40, v40
	v_fma_f32 v41, -v40, v5, v84
	v_cvt_i32_f32_e32 v40, v40
	v_cmp_ge_f32_e64 s[4:5], |v41|, v5
	s_and_b64 s[4:5], s[4:5], exec
	s_cselect_b32 s4, s33, 0
	v_readfirstlane_b32 s5, v40
	s_add_i32 s4, s5, s4
	s_sext_i32_i16 s44, s4
	s_mul_i32 s4, s4, s31
	s_sub_i32 s4, s30, s4
	s_sext_i32_i16 s4, s4
	s_lshl_b32 s42, s44, 6
	s_lshl_b32 s4, s4, 5
	s_cmp_eq_u64 s[50:51], 0
	s_cbranch_scc1 .LBB0_26
; __device__ __forceinline__ unsigned f2bf(float f) { unsigned u = __builtin_bit_cast(unsigned, f); return (u + 0x7fffu + ((u >> 16) & 1u)) >> 16; }
; __device__ __forceinline__ void p0_finish(const TDesc& d, float (&wv)[32], LAS float* scr, int lane) {
;     ...
;     if (d.gsc) {
;         float c1 = 0.f, c2 = 0.f;
; #pragma unroll
;         for (int i = 0; i < 32; ++i) { const int k = k0 + 2 * i + (lane >> 5); c2 += d.bsc[k] * wv[i]; wv[i] *= d.gsc[k]; c1 += bf2f((unsigned short)f2bf(wv[i])); }
;         c1 += __shfl_xor(c1, 32); c2 += __shfl_xor(c2, 32);
	v_add_u32_e32 v40, s42, v76
	v_ashrrev_i32_e32 v41, 31, v40
	v_lshlrev_b64 v[40:41], 2, v[40:41]
	v_lshl_add_u64 v[42:43], s[52:53], 0, v[40:41]
	v_lshl_add_u64 v[40:41], s[50:51], 0, v[40:41]
	global_load_dword v5, v[42:43], off nt
	global_load_dword v64, v[42:43], off offset:8 nt
	global_load_dword v44, v[40:41], off nt
	global_load_dword v45, v[40:41], off offset:8 nt
	global_load_dword v65, v[42:43], off offset:16 nt
	global_load_dword v66, v[42:43], off offset:24 nt
	global_load_dword v46, v[40:41], off offset:16 nt
	global_load_dword v47, v[40:41], off offset:24 nt
	global_load_dword v67, v[42:43], off offset:32 nt
	global_load_dword v68, v[42:43], off offset:40 nt
	global_load_dword v48, v[40:41], off offset:32 nt
	global_load_dword v49, v[40:41], off offset:40 nt
	global_load_dword v69, v[42:43], off offset:48 nt
	global_load_dword v70, v[42:43], off offset:56 nt
	global_load_dword v50, v[40:41], off offset:48 nt
	global_load_dword v51, v[40:41], off offset:56 nt
	global_load_dword v71, v[42:43], off offset:64 nt
	global_load_dword v72, v[42:43], off offset:72 nt
	global_load_dword v52, v[40:41], off offset:64 nt
	global_load_dword v53, v[40:41], off offset:72 nt
	global_load_dword v73, v[42:43], off offset:80 nt
	global_load_dword v74, v[42:43], off offset:88 nt
	global_load_dword v54, v[40:41], off offset:80 nt
	global_load_dword v55, v[40:41], off offset:88 nt
	global_load_dword v75, v[42:43], off offset:96 nt
	global_load_dword v84, v[42:43], off offset:104 nt
	global_load_dword v85, v[42:43], off offset:112 nt
	global_load_dword v86, v[42:43], off offset:120 nt
	global_load_dword v56, v[40:41], off offset:96 nt
	global_load_dword v57, v[40:41], off offset:104 nt
	global_load_dword v58, v[40:41], off offset:112 nt
	global_load_dword v59, v[40:41], off offset:120 nt
	global_load_dword v87, v[42:43], off offset:128 nt
	global_load_dword v88, v[42:43], off offset:136 nt
	global_load_dword v89, v[42:43], off offset:144 nt
	global_load_dword v90, v[42:43], off offset:152 nt
	global_load_dword v60, v[40:41], off offset:128 nt
	global_load_dword v61, v[40:41], off offset:136 nt
	global_load_dword v62, v[40:41], off offset:144 nt
	global_load_dword v63, v[40:41], off offset:152 nt
	s_waitcnt vmcnt(39)
	v_fma_f32 v5, v8, v5, 0
	s_waitcnt vmcnt(38)
	v_fmac_f32_e32 v5, v9, v64
	s_waitcnt vmcnt(36)
	v_pk_mul_f32 v[8:9], v[8:9], v[44:45]
	s_nop 0
	v_bfe_u32 v44, v8, 16, 1
	s_waitcnt vmcnt(35)
	v_fmac_f32_e32 v5, v10, v65
	v_bfe_u32 v45, v9, 16, 1
	v_add3_u32 v44, v8, v44, s28
	s_waitcnt vmcnt(34)
	v_fmac_f32_e32 v5, v11, v66
	s_waitcnt vmcnt(32)
	v_pk_mul_f32 v[10:11], v[10:11], v[46:47]
	v_add3_u32 v45, v9, v45, s28
	v_and_b32_e32 v44, 0xffff0000, v44
	v_bfe_u32 v46, v10, 16, 1
	v_bfe_u32 v47, v11, 16, 1
	s_waitcnt vmcnt(31)
	v_fmac_f32_e32 v5, v12, v67
	v_and_b32_e32 v45, 0xffff0000, v45
	v_add_f32_e32 v44, 0, v44
	v_add3_u32 v46, v10, v46, s28
	v_add3_u32 v47, v11, v47, s28
	s_waitcnt vmcnt(30)
	v_fmac_f32_e32 v5, v13, v68
	s_waitcnt vmcnt(28)
	v_pk_mul_f32 v[12:13], v[12:13], v[48:49]
	v_add_f32_e32 v44, v44, v45
	v_and_b32_e32 v45, 0xffff0000, v46
	v_and_b32_e32 v46, 0xffff0000, v47
	v_bfe_u32 v47, v12, 16, 1
	v_bfe_u32 v48, v13, 16, 1
	s_waitcnt vmcnt(27)
	v_fmac_f32_e32 v5, v14, v69
	v_add_f32_e32 v44, v44, v45
	v_add3_u32 v45, v12, v47, s28
	v_add3_u32 v47, v13, v48, s28
	s_waitcnt vmcnt(26)
	v_fmac_f32_e32 v5, v15, v70
	s_waitcnt vmcnt(24)
	v_pk_mul_f32 v[14:15], v[14:15], v[50:51]
	v_add_f32_e32 v44, v44, v46
	v_and_b32_e32 v45, 0xffff0000, v45
	v_and_b32_e32 v46, 0xffff0000, v47
	v_bfe_u32 v47, v14, 16, 1
	v_bfe_u32 v48, v15, 16, 1
	s_waitcnt vmcnt(23)
	v_fmac_f32_e32 v5, v16, v71
	v_add_f32_e32 v44, v44, v45
	v_add3_u32 v45, v14, v47, s28
	v_add3_u32 v47, v15, v48, s28
	s_waitcnt vmcnt(22)
	v_fmac_f32_e32 v5, v17, v72
	s_waitcnt vmcnt(20)
	v_pk_mul_f32 v[16:17], v[16:17], v[52:53]
	v_add_f32_e32 v44, v44, v46
	v_and_b32_e32 v45, 0xffff0000, v45
	v_and_b32_e32 v46, 0xffff0000, v47
	v_bfe_u32 v47, v16, 16, 1
	v_add_f32_e32 v44, v44, v45
	v_add3_u32 v45, v16, v47, s28
	v_add_f32_e32 v44, v44, v46
	v_and_b32_e32 v45, 0xffff0000, v45
	v_add_f32_e32 v46, v44, v45
	global_load_dword v64, v[42:43], off offset:160 nt
	global_load_dword v65, v[42:43], off offset:168 nt
	global_load_dword v44, v[40:41], off offset:160 nt
	global_load_dword v45, v[40:41], off offset:168 nt
	v_bfe_u32 v48, v17, 16, 1
	v_add3_u32 v47, v17, v48, s28
	s_waitcnt vmcnt(23)
	v_fmac_f32_e32 v5, v18, v73
	v_and_b32_e32 v47, 0xffff0000, v47
	s_waitcnt vmcnt(22)
	v_fmac_f32_e32 v5, v19, v74
	s_waitcnt vmcnt(20)
	v_pk_mul_f32 v[18:19], v[18:19], v[54:55]
	v_add_f32_e32 v48, v46, v47
	v_bfe_u32 v46, v18, 16, 1
	v_add3_u32 v49, v18, v46, s28
	global_load_dword v54, v[42:43], off offset:176 nt
	global_load_dword v55, v[42:43], off offset:184 nt
	global_load_dword v46, v[40:41], off offset:176 nt
	global_load_dword v47, v[40:41], off offset:184 nt
	v_and_b32_e32 v49, 0xffff0000, v49
	v_add_f32_e32 v48, v48, v49
	v_bfe_u32 v49, v19, 16, 1
	v_add3_u32 v49, v19, v49, s28
	v_and_b32_e32 v49, 0xffff0000, v49
	v_add_f32_e32 v50, v48, v49
	global_load_dword v66, v[42:43], off offset:192 nt
	global_load_dword v67, v[42:43], off offset:200 nt
	global_load_dword v48, v[40:41], off offset:192 nt
	global_load_dword v49, v[40:41], off offset:200 nt
	s_waitcnt vmcnt(27)
	v_fmac_f32_e32 v5, v20, v75
	s_waitcnt vmcnt(26)
; __device__ __forceinline__ unsigned f2bf(float f) { unsigned u = __builtin_bit_cast(unsigned, f); return (u + 0x7fffu + ((u >> 16) & 1u)) >> 16; }
; __device__ __forceinline__ void p0_finish(const TDesc& d, float (&wv)[32], LAS float* scr, int lane) {
;     ...
;     if (d.gsc) {
;         float c1 = 0.f, c2 = 0.f;
; #pragma unroll
;         for (int i = 0; i < 32; ++i) { const int k = k0 + 2 * i + (lane >> 5); c2 += d.bsc[k] * wv[i]; wv[i] *= d.gsc[k]; c1 += bf2f((unsigned short)f2bf(wv[i])); }
;         c1 += __shfl_xor(c1, 32); c2 += __shfl_xor(c2, 32);
;         if (lane < 32) { float* p = d.cvp + (size_t)kb * 2 * 4096 + n0 + lane; p[0] = c1; p[4096] = c2; }
	v_fmac_f32_e32 v5, v21, v84
	s_waitcnt vmcnt(22)
	v_pk_mul_f32 v[20:21], v[20:21], v[56:57]
	v_fmac_f32_e32 v5, v22, v85
	v_bfe_u32 v51, v20, 16, 1
	v_add3_u32 v51, v20, v51, s28
	v_and_b32_e32 v51, 0xffff0000, v51
	v_add_f32_e32 v52, v50, v51
	global_load_dword v56, v[42:43], off offset:208 nt
	global_load_dword v57, v[42:43], off offset:216 nt
	global_load_dword v50, v[40:41], off offset:208 nt
	global_load_dword v51, v[40:41], off offset:216 nt
	v_bfe_u32 v53, v21, 16, 1
	v_add3_u32 v53, v21, v53, s28
	v_and_b32_e32 v53, 0xffff0000, v53
	v_fmac_f32_e32 v5, v23, v86
	s_waitcnt vmcnt(24)
	v_pk_mul_f32 v[22:23], v[22:23], v[58:59]
	v_add_f32_e32 v68, v52, v53
	v_bfe_u32 v58, v22, 16, 1
	global_load_dword v59, v[42:43], off offset:224 nt
	global_load_dword v69, v[42:43], off offset:232 nt
	global_load_dword v52, v[40:41], off offset:224 nt
	global_load_dword v53, v[40:41], off offset:232 nt
	v_add3_u32 v58, v22, v58, s28
	v_and_b32_e32 v58, 0xffff0000, v58
	v_add_f32_e32 v58, v68, v58
	v_bfe_u32 v68, v23, 16, 1
	v_add3_u32 v68, v23, v68, s28
	v_and_b32_e32 v68, 0xffff0000, v68
	v_add_f32_e32 v58, v58, v68
	global_load_dword v68, v[42:43], off offset:240 nt
	global_load_dword v70, v[42:43], off offset:248 nt
	s_nop 0
	global_load_dword v42, v[40:41], off offset:240 nt
	global_load_dword v43, v[40:41], off offset:248 nt
	s_waitcnt vmcnt(31)
	v_fmac_f32_e32 v5, v24, v87
	s_waitcnt vmcnt(30)
	v_fmac_f32_e32 v5, v25, v88
	s_waitcnt vmcnt(26)
	v_pk_mul_f32 v[24:25], v[24:25], v[60:61]
	v_fmac_f32_e32 v5, v26, v89
	v_bfe_u32 v40, v24, 16, 1
	v_add3_u32 v40, v24, v40, s28
	v_bfe_u32 v41, v25, 16, 1
	v_and_b32_e32 v40, 0xffff0000, v40
	v_add3_u32 v41, v25, v41, s28
	v_add_f32_e32 v40, v58, v40
	v_and_b32_e32 v41, 0xffff0000, v41
	v_fmac_f32_e32 v5, v27, v90
	s_waitcnt vmcnt(24)
	v_pk_mul_f32 v[26:27], v[26:27], v[62:63]
	v_add_f32_e32 v40, v40, v41
	v_bfe_u32 v41, v26, 16, 1
	v_add3_u32 v41, v26, v41, s28
	v_and_b32_e32 v41, 0xffff0000, v41
	v_add_f32_e32 v40, v40, v41
	v_bfe_u32 v41, v27, 16, 1
	v_add3_u32 v41, v27, v41, s28
	v_and_b32_e32 v41, 0xffff0000, v41
	v_add_f32_e32 v40, v40, v41
	s_waitcnt vmcnt(23)
	v_fmac_f32_e32 v5, v28, v64
	s_waitcnt vmcnt(22)
	v_fmac_f32_e32 v5, v29, v65
	s_waitcnt vmcnt(20)
	v_pk_mul_f32 v[28:29], v[28:29], v[44:45]
	s_nop 0
	v_bfe_u32 v41, v28, 16, 1
	v_add3_u32 v41, v28, v41, s28
	v_and_b32_e32 v41, 0xffff0000, v41
	v_add_f32_e32 v40, v40, v41
	v_bfe_u32 v41, v29, 16, 1
	v_add3_u32 v41, v29, v41, s28
	s_waitcnt vmcnt(19)
	v_fmac_f32_e32 v5, v30, v54
	v_and_b32_e32 v41, 0xffff0000, v41
	s_waitcnt vmcnt(18)
	v_fmac_f32_e32 v5, v31, v55
	s_waitcnt vmcnt(16)
	v_pk_mul_f32 v[30:31], v[30:31], v[46:47]
	v_add_f32_e32 v40, v40, v41
	v_bfe_u32 v41, v30, 16, 1
	v_add3_u32 v41, v30, v41, s28
	v_and_b32_e32 v41, 0xffff0000, v41
	v_add_f32_e32 v40, v40, v41
	v_bfe_u32 v41, v31, 16, 1
	v_add3_u32 v41, v31, v41, s28
	s_waitcnt vmcnt(15)
	v_fmac_f32_e32 v5, v32, v66
	v_and_b32_e32 v41, 0xffff0000, v41
	s_waitcnt vmcnt(14)
	v_fmac_f32_e32 v5, v33, v67
	s_waitcnt vmcnt(12)
	v_pk_mul_f32 v[32:33], v[32:33], v[48:49]
	v_add_f32_e32 v40, v40, v41
	v_bfe_u32 v41, v32, 16, 1
	v_add3_u32 v41, v32, v41, s28
	v_and_b32_e32 v41, 0xffff0000, v41
	v_add_f32_e32 v40, v40, v41
	v_bfe_u32 v41, v33, 16, 1
	v_add3_u32 v41, v33, v41, s28
	s_waitcnt vmcnt(11)
	v_fmac_f32_e32 v5, v34, v56
	v_and_b32_e32 v41, 0xffff0000, v41
	s_waitcnt vmcnt(10)
	v_fmac_f32_e32 v5, v35, v57
	s_waitcnt vmcnt(8)
	v_pk_mul_f32 v[34:35], v[34:35], v[50:51]
	v_add_f32_e32 v40, v40, v41
	v_bfe_u32 v41, v34, 16, 1
	v_add3_u32 v41, v34, v41, s28
	v_and_b32_e32 v41, 0xffff0000, v41
	v_add_f32_e32 v40, v40, v41
	v_bfe_u32 v41, v35, 16, 1
	v_add3_u32 v41, v35, v41, s28
	s_waitcnt vmcnt(7)
	v_fmac_f32_e32 v5, v36, v59
	v_and_b32_e32 v41, 0xffff0000, v41
	s_waitcnt vmcnt(6)
	v_fmac_f32_e32 v5, v37, v69
	s_waitcnt vmcnt(4)
	v_pk_mul_f32 v[36:37], v[36:37], v[52:53]
	v_add_f32_e32 v40, v40, v41
	v_bfe_u32 v41, v36, 16, 1
	v_add3_u32 v41, v36, v41, s28
	v_and_b32_e32 v41, 0xffff0000, v41
	v_add_f32_e32 v40, v40, v41
	v_bfe_u32 v41, v37, 16, 1
	v_add3_u32 v41, v37, v41, s28
	s_waitcnt vmcnt(3)
	v_fmac_f32_e32 v5, v38, v68
	v_and_b32_e32 v41, 0xffff0000, v41
	s_waitcnt vmcnt(2)
	v_fmac_f32_e32 v5, v39, v70
	s_waitcnt vmcnt(0)
	v_pk_mul_f32 v[38:39], v[38:39], v[42:43]
	v_add_f32_e32 v40, v40, v41
	v_bfe_u32 v41, v38, 16, 1
	v_add3_u32 v41, v38, v41, s28
	v_and_b32_e32 v41, 0xffff0000, v41
	v_add_f32_e32 v40, v40, v41
	v_bfe_u32 v41, v39, 16, 1
	v_add3_u32 v41, v39, v41, s28
	v_and_b32_e32 v41, 0xffff0000, v41
	v_and_b32_e32 v42, 64, v83
	v_add_f32_e32 v40, v40, v41
	v_xor_b32_e32 v41, 32, v83
	v_add_u32_e32 v42, 64, v42
	v_cmp_lt_i32_e32 vcc, v41, v42
	s_nop 1
	v_cndmask_b32_e32 v41, v83, v41, vcc
	v_lshlrev_b32_e32 v42, 2, v41
	ds_bpermute_b32 v41, v42, v40
	ds_bpermute_b32 v42, v42, v5
	s_and_saveexec_b64 s[48:49], s[0:1]
	s_cbranch_execz .LBB0_25
	s_ashr_i32 s45, s44, 31
	s_lshl_b64 s[30:31], s[44:45], 15
	s_add_u32 s33, s46, s30
	s_addc_u32 s36, s47, s31
	s_ashr_i32 s5, s4, 31
	s_lshl_b64 s[30:31], s[4:5], 2
	s_add_u32 s30, s33, s30
	s_addc_u32 s31, s36, s31
	s_waitcnt lgkmcnt(0)
	v_add_f32_e32 v5, v5, v42
	v_add_f32_e32 v42, v40, v41
	v_lshl_add_u64 v[40:41], v[0:1], 2, s[30:31]
	global_store_dword v[40:41], v42, off
	v_add_co_u32_e32 v40, vcc, 0x4000, v40
	s_nop 1
	v_addc_co_u32_e32 v41, vcc, 0, v41, vcc
	global_store_dword v[40:41], v5, off
	s_branch .LBB0_25

; __device__ __forceinline__ u32x2 pk4(f32x4 v) { u32x2 r; r.x = pk2(v.x, v.y); r.y = pk2(v.z, v.w); return r; }
; __global__ void __launch_bounds__(NWAVES * 64, 2) mega(Args args) {
;     ...
;         for (int row = gw; row < MR + 2048; row += NGW) {
;             const float* src = row < MP ? args.in[0] + (size_t)row * DM : (row < MR ? args.in[1] + (size_t)(row - MP) * DM : args.in[6] + (size_t)(row - MR) * DM);
;             bf16_t* dstp = row < MR ? XB + (size_t)row * DM : MEMB + (size_t)(row - MR) * DM;
;             const f32x4* s4 = (const f32x4*)src + lane; u32x2* ob = (u32x2*)dstp + lane;
; #pragma unroll
;             for (int j = 0; j < 4; ++j) ob[64 * j] = pk4(s4[64 * j]);
;         }
.LBB0_101:
	s_lshl_b64 s[4:5], s[4:5], 12
	s_add_u32 s0, s0, s4
	s_addc_u32 s1, s1, s5
	v_lshl_add_u64 v[6:7], v[0:1], 4, s[0:1]
	global_load_dwordx4 v[2:5], v[6:7], off nt
	s_add_i32 s0, s6, 0xffffbf80
	s_ashr_i32 s1, s6, 31
	s_cmpk_lt_i32 s6, 0x4080
	s_cselect_b32 s0, s6, s0
	v_readlane_b32 s6, v251, 58
	s_cselect_b32 s1, s1, 0
	v_readlane_b32 s4, v251, 57
	v_readlane_b32 s7, v251, 59
	v_readlane_b32 s5, v251, 56
	s_cselect_b32 s4, s7, s4
	s_cselect_b32 s5, s6, s5
	s_lshl_b64 s[0:1], s[0:1], 11
	s_add_u32 s0, s5, s0
	s_addc_u32 s1, s4, s1
	v_lshl_add_u64 v[8:9], v[0:1], 3, s[0:1]
	s_mov_b32 s6, s28
	s_waitcnt vmcnt(0)
	v_cvt_pk_bf16_f32 v2, v2, v3
	v_cvt_pk_bf16_f32 v3, v4, v5
	global_store_dwordx2 v[8:9], v[2:3], off
	global_load_dwordx4 v[2:5], v[6:7], off offset:1024 nt
	s_waitcnt vmcnt(0)
	v_cvt_pk_bf16_f32 v2, v2, v3
	v_cvt_pk_bf16_f32 v3, v4, v5
	global_store_dwordx2 v[8:9], v[2:3], off offset:512
	global_load_dwordx4 v[2:5], v[6:7], off offset:2048 nt
	s_waitcnt vmcnt(0)
	v_cvt_pk_bf16_f32 v2, v2, v3
	v_cvt_pk_bf16_f32 v3, v4, v5
	global_store_dwordx2 v[8:9], v[2:3], off offset:1024
	global_load_dwordx4 v[2:5], v[6:7], off offset:3072 nt
	s_waitcnt vmcnt(0)
	v_cvt_pk_bf16_f32 v2, v2, v3
	v_cvt_pk_bf16_f32 v3, v4, v5
	global_store_dwordx2 v[8:9], v[2:3], off offset:1536

; __device__ __forceinline__ unsigned f2bf(float f) { unsigned u = __builtin_bit_cast(unsigned, f); return (u + 0x7fffu + ((u >> 16) & 1u)) >> 16; }
; __device__ __forceinline__ u32x2 pk4(f32x4 v) { u32x2 r; r.x = pk2(v.x, v.y); r.y = pk2(v.z, v.w); return r; }
; __global__ void __launch_bounds__(NWAVES * 64, 2) mega(Args args) {
;     ...
;         for (int row = gw; row < MR + 2048; row += NGW) {
;             const float* src = row < MP ? args.in[0] + (size_t)row * DM : (row < MR ? args.in[1] + (size_t)(row - MP) * DM : args.in[6] + (size_t)(row - MR) * DM);
;             bf16_t* dstp = row < MR ? XB + (size_t)row * DM : MEMB + (size_t)(row - MR) * DM;
;             const f32x4* s4 = (const f32x4*)src + lane; u32x2* ob = (u32x2*)dstp + lane;
; #pragma unroll
;             for (int j = 0; j < 4; ++j) ob[64 * j] = pk4(s4[64 * j]);
;         }
;         for (int e = bx * 512 + tid; e < DEPTH * 4 * 128 * 128; e += G * 512) { const int s = e & 127, t = (e >> 7) & 127; WSP[e] = s <= t ? (bf16_t)f2bf(args.in[10][e]) : (bf16_t)0; }
.LBB0_106:
	v_and_b32_e32 v3, 0x7f, v1
	v_bfe_u32 v8, v1, 7, 7
	v_cmp_le_u32_e32 vcc, v3, v8
	v_mov_b32_e32 v3, 0
	s_and_saveexec_b64 s[20:21], vcc
	s_cbranch_execz .LBB0_105
	global_load_dword v3, v[6:7], off nt
	s_waitcnt vmcnt(0)
	v_bfe_u32 v8, v3, 16, 1
	v_add3_u32 v3, v3, v8, s9
	v_lshrrev_b32_e32 v3, 16, v3
	s_branch .LBB0_105
.LBB0_108:
	s_lshl_b64 s[22:23], s[22:23], 12
	s_add_u32 s6, s6, s22
	s_addc_u32 s7, s7, s23
	v_lshl_add_u64 v[6:7], v[0:1], 4, s[6:7]
	global_load_dwordx4 v[2:5], v[6:7], off nt
	global_load_dwordx4 v[180:183], v[6:7], off offset:1024 nt
	global_load_dwordx4 v[184:187], v[6:7], off offset:2048 nt
	global_load_dwordx4 v[188:191], v[6:7], off offset:3072 nt
	s_add_i32 s0, s4, 0xffffbf80
	s_ashr_i32 s5, s4, 31
	s_cmpk_lt_i32 s4, 0x4080
	v_readlane_b32 s22, v251, 58
	s_cselect_b32 s7, s5, 0
	s_cselect_b32 s6, s4, s0
	v_readlane_b32 s0, v251, 57
	v_readlane_b32 s23, v251, 59
	v_readlane_b32 s5, v251, 56
	s_cselect_b32 s0, s23, s0
	s_cselect_b32 s5, s22, s5
	s_lshl_b64 s[6:7], s[6:7], 11
	s_add_u32 s6, s5, s6
	s_addc_u32 s7, s0, s7
	v_lshl_add_u64 v[8:9], v[0:1], 3, s[6:7]
	s_add_i32 s6, s4, s90
	s_cmpk_gt_i32 s6, 0x487f
	s_waitcnt vmcnt(3)
	v_cvt_pk_bf16_f32 v2, v2, v3
	v_cvt_pk_bf16_f32 v3, v4, v5
	global_store_dwordx2 v[8:9], v[2:3], off
	s_waitcnt vmcnt(2)
	v_cvt_pk_bf16_f32 v180, v180, v181
	v_cvt_pk_bf16_f32 v181, v182, v183
	global_store_dwordx2 v[8:9], v[180:181], off offset:512
	s_waitcnt vmcnt(1)
	v_cvt_pk_bf16_f32 v184, v184, v185
	v_cvt_pk_bf16_f32 v185, v186, v187
	global_store_dwordx2 v[8:9], v[184:185], off offset:1024
	s_waitcnt vmcnt(0)
	v_cvt_pk_bf16_f32 v188, v188, v189
	v_cvt_pk_bf16_f32 v189, v190, v191
	global_store_dwordx2 v[8:9], v[188:189], off offset:1536
	s_cbranch_scc1 .LBB0_103

; __device__ __forceinline__ u32x2 pk4(f32x4 v) { u32x2 r; r.x = pk2(v.x, v.y); r.y = pk2(v.z, v.w); return r; }
; __global__ void __launch_bounds__(NWAVES * 64, 2) mega(Args args) {
;     ...
;         for (int row = gw; row < MR + 2048; row += NGW) {
;             const float* src = row < MP ? args.in[0] + (size_t)row * DM : (row < MR ? args.in[1] + (size_t)(row - MP) * DM : args.in[6] + (size_t)(row - MR) * DM);
;             bf16_t* dstp = row < MR ? XB + (size_t)row * DM : MEMB + (size_t)(row - MR) * DM;
;             const f32x4* s4 = (const f32x4*)src + lane; u32x2* ob = (u32x2*)dstp + lane;
; #pragma unroll
;             for (int j = 0; j < 4; ++j) ob[64 * j] = pk4(s4[64 * j]);
;         }
.LBB0_117:
	s_lshl_b64 s[22:23], s[22:23], 12
	s_add_u32 s4, s4, s22
	s_addc_u32 s5, s5, s23
	v_lshl_add_u64 v[6:7], v[0:1], 4, s[4:5]
	global_load_dwordx4 v[2:5], v[6:7], off nt
	global_load_dwordx4 v[180:183], v[6:7], off offset:1024 nt
	global_load_dwordx4 v[184:187], v[6:7], off offset:2048 nt
	global_load_dwordx4 v[188:191], v[6:7], off offset:3072 nt
	s_add_i32 s0, s6, 0xffffbf80
	s_ashr_i32 s4, s6, 31
	s_cmpk_lt_i32 s6, 0x4080
	v_readlane_b32 s22, v251, 58
	s_cselect_b32 s5, s4, 0
	s_cselect_b32 s4, s6, s0
	v_readlane_b32 s0, v251, 57
	v_readlane_b32 s23, v251, 59
	v_readlane_b32 s7, v251, 56
	s_cselect_b32 s0, s23, s0
	s_cselect_b32 s7, s22, s7
	s_lshl_b64 s[4:5], s[4:5], 11
	s_add_u32 s4, s7, s4
	s_addc_u32 s5, s0, s5
	v_lshl_add_u64 v[8:9], v[0:1], 3, s[4:5]
	s_add_i32 s4, s6, s90
	s_cmpk_lt_i32 s4, 0x4000
	s_waitcnt vmcnt(3)
	v_cvt_pk_bf16_f32 v2, v2, v3
	v_cvt_pk_bf16_f32 v3, v4, v5
	global_store_dwordx2 v[8:9], v[2:3], off
	s_waitcnt vmcnt(2)
	v_cvt_pk_bf16_f32 v180, v180, v181
	v_cvt_pk_bf16_f32 v181, v182, v183
	global_store_dwordx2 v[8:9], v[180:181], off offset:512
	s_waitcnt vmcnt(1)
	v_cvt_pk_bf16_f32 v184, v184, v185
	v_cvt_pk_bf16_f32 v185, v186, v187
	global_store_dwordx2 v[8:9], v[184:185], off offset:1024
	s_waitcnt vmcnt(0)
	v_cvt_pk_bf16_f32 v188, v188, v189
	v_cvt_pk_bf16_f32 v189, v190, v191
	global_store_dwordx2 v[8:9], v[188:189], off offset:1536
	s_cbranch_scc1 .LBB0_120
	s_cmpk_lt_u32 s4, 0x4080
	s_cbranch_scc1 .LBB0_121
	s_add_i32 s0, s4, 0xffffbf80
	s_mov_b64 s[6:7], s[20:21]
	s_mov_b64 s[22:23], s[0:1]
	s_cbranch_execz .LBB0_122
	s_branch .LBB0_123

; __device__ __forceinline__ void final_ln(const bf16_t* ZB, const float* gam, const float* bet, float* yout, int gw, int NGW, int lane) {
;     f32x4 gv[4], bv[4];
; #pragma unroll
;     for (int j = 0; j < 4; ++j) { gv[j] = *(const f32x4*)(gam + 4 * lane + 256 * j); bv[j] = *(const f32x4*)(bet + 4 * lane + 256 * j); }
;     for (int row = gw; row < MR; row += NGW) {
;         const u32x2* zr = (const u32x2*)(ZB + (size_t)row * DM) + lane;
;         f32x4 v[4]; float s = 0.f;
; #pragma unroll
;         for (int j = 0; j < 4; ++j) { const u32x2 raw = zr[64 * j]; v[j] = (f32x4){bflo(raw.x), bfhi(raw.x), bflo(raw.y), bfhi(raw.y)}; s += (v[j].x + v[j].y) + (v[j].z + v[j].w); }
.LBB0_2455:
	s_cmp_lt_i32 s24, 18
	s_cselect_b64 s[0:1], -1, 0
	s_cmp_gt_i32 s25, 17
	s_cselect_b64 s[2:3], -1, 0
	s_and_b64 s[2:3], s[0:1], s[2:3]
	v_readlane_b32 s18, v251, 63
	v_readlane_b32 s20, v253, 20
	s_andn2_b64 vcc, exec, s[2:3]
	v_readlane_b32 s19, v252, 0
	v_readlane_b32 s6, v250, 18
	v_readlane_b32 s21, v253, 21
	s_cbranch_vccnz .LBB0_2459
	v_readlane_b32 s2, v251, 38
	v_mbcnt_lo_u32_b32 v34, -1, 0
	v_mbcnt_hi_u32_b32 v34, -1, v34
	s_cmpk_lt_i32 s2, 0x4080
	v_readlane_b32 s3, v251, 39
	s_cbranch_scc0 .LBB0_2459
	v_lshlrev_b32_e32 v0, 2, v34
	v_readlane_b32 s36, v251, 22
	v_ashrrev_i32_e32 v1, 31, v0
	v_readlane_b32 s48, v251, 34
	v_readlane_b32 s49, v251, 35
	v_lshlrev_b64 v[0:1], 2, v[0:1]
	v_readlane_b32 s50, v251, 36
	v_readlane_b32 s51, v251, 37
	s_mov_b64 s[12:13], s[48:49]
	s_mov_b64 s[14:15], s[50:51]
	v_lshl_add_u64 v[2:3], s[12:13], 0, v[0:1]
	v_lshl_add_u64 v[4:5], s[14:15], 0, v[0:1]
	v_add_co_u32_e32 v0, vcc, 0x1000, v2
	s_mov_b32 s8, s2
	s_mov_b64 s[2:3], 0x1000
	v_addc_co_u32_e32 v1, vcc, 0, v3, vcc
	v_lshl_add_u64 v[28:29], v[4:5], 0, s[2:3]
	v_add_co_u32_e32 v4, vcc, 0x1000, v4
	v_lshl_add_u64 v[24:25], v[2:3], 0, s[2:3]
	s_nop 0
	v_addc_co_u32_e32 v5, vcc, 0, v5, vcc
	global_load_dwordx4 v[0:3], v[0:1], off
	s_waitcnt lgkmcnt(0)
	global_load_dwordx4 v[4:7], v[4:5], off
	s_nop 0
	global_load_dwordx4 v[8:11], v[24:25], off offset:1024
	global_load_dwordx4 v[12:15], v[24:25], off offset:2048
	global_load_dwordx4 v[16:19], v[28:29], off offset:1024
	global_load_dwordx4 v[20:23], v[28:29], off offset:2048
	s_nop 0
	global_load_dwordx4 v[24:27], v[24:25], off offset:3072
	s_nop 0
	global_load_dwordx4 v[28:31], v[28:29], off offset:3072
	v_and_b32_e32 v32, 64, v219
	v_add_u32_e32 v32, 64, v32
	v_xor_b32_e32 v33, 1, v219
	v_cmp_lt_i32_e32 vcc, v33, v32
	s_ashr_i32 s9, s8, 31
	v_readlane_b32 s12, v250, 10
	v_cndmask_b32_e32 v33, v219, v33, vcc
	v_lshlrev_b32_e32 v36, 2, v33
	v_xor_b32_e32 v33, 2, v219
	v_cmp_lt_i32_e32 vcc, v33, v32
	s_lshl_b64 s[2:3], s[8:9], 11
	v_readlane_b32 s14, v250, 12
	v_cndmask_b32_e32 v33, v219, v33, vcc
	v_lshlrev_b32_e32 v37, 2, v33
	v_xor_b32_e32 v33, 4, v219
	v_cmp_lt_i32_e32 vcc, v33, v32
	v_readlane_b32 s15, v250, 13
	s_add_u32 s2, s14, s2
	v_cndmask_b32_e32 v33, v219, v33, vcc
	v_lshlrev_b32_e32 v38, 2, v33
	v_xor_b32_e32 v33, 8, v219
	v_cmp_lt_i32_e32 vcc, v33, v32
	v_ashrrev_i32_e32 v35, 31, v34
	s_addc_u32 s3, s15, s3
	v_cndmask_b32_e32 v33, v219, v33, vcc
	v_lshlrev_b32_e32 v39, 2, v33
	v_xor_b32_e32 v33, 16, v219
	v_cmp_lt_i32_e32 vcc, v33, v32
	v_readlane_b32 s10, v250, 2
	v_readlane_b32 s11, v250, 3
	v_cndmask_b32_e32 v33, v219, v33, vcc
	v_lshlrev_b32_e32 v40, 2, v33
	v_xor_b32_e32 v33, 32, v219
	v_cmp_lt_i32_e32 vcc, v33, v32
	s_lshl_b64 s[4:5], s[8:9], 12
	v_readlane_b32 s13, v250, 11
	v_cndmask_b32_e32 v32, v219, v33, vcc
	v_lshlrev_b32_e32 v41, 2, v32
	v_lshl_add_u64 v[32:33], v[34:35], 3, s[2:3]
	s_mov_b64 s[2:3], 0x5b34100
	v_lshl_add_u64 v[32:33], v[32:33], 0, s[2:3]
	s_lshl_b64 s[2:3], s[10:11], 11
	s_add_u32 s4, s12, s4
	s_addc_u32 s5, s13, s5
	v_lshl_add_u64 v[34:35], v[34:35], 4, s[4:5]
	s_mov_b64 s[4:5], 0xc00
	v_lshl_add_u64 v[34:35], v[34:35], 0, s[4:5]
	v_readlane_b32 s4, v250, 4
	v_mov_b32_e32 v42, 0x3727c5ac
	v_readlane_b32 s5, v250, 5
	v_readlane_b32 s37, v251, 23
	v_readlane_b32 s38, v251, 24
	v_readlane_b32 s39, v251, 25
	v_readlane_b32 s40, v251, 26
	v_readlane_b32 s41, v251, 27
	v_readlane_b32 s42, v251, 28
	v_readlane_b32 s43, v251, 29
	v_readlane_b32 s44, v251, 30
	v_readlane_b32 s45, v251, 31
	v_readlane_b32 s46, v251, 32
	v_readlane_b32 s47, v251, 33
	global_load_dwordx2 v[44:45], v[32:33], off nt
	global_load_dwordx2 v[46:47], v[32:33], off offset:512 nt
	global_load_dwordx2 v[48:49], v[32:33], off offset:1024 nt
	global_load_dwordx2 v[50:51], v[32:33], off offset:1536 nt
	v_lshl_add_u64 v[32:33], v[32:33], 0, s[2:3]
	s_waitcnt vmcnt(0)
; __device__ __forceinline__ void final_ln(const bf16_t* ZB, const float* gam, const float* bet, float* yout, int gw, int NGW, int lane) {
;     ...
;     for (int row = gw; row < MR; row += NGW) {
;         const u32x2* zr = (const u32x2*)(ZB + (size_t)row * DM) + lane;
;         f32x4 v[4]; float s = 0.f;
; #pragma unroll
;         for (int j = 0; j < 4; ++j) { const u32x2 raw = zr[64 * j]; v[j] = (f32x4){bflo(raw.x), bfhi(raw.x), bflo(raw.y), bfhi(raw.y)}; s += (v[j].x + v[j].y) + (v[j].z + v[j].w); }
;         const float mean = wave_sum(s) * (1.f / DM); float s2 = 0.f;
; #pragma unroll
;         for (int j = 0; j < 4; ++j) { v[j] = v[j] - mean; s2 += (v[j].x * v[j].x + v[j].y * v[j].y) + (v[j].z * v[j].z + v[j].w * v[j].w); }
;         const float rstd = __builtin_amdgcn_rsqf(wave_sum(s2) * (1.f / DM) + LN_EPS);
;         f32x4* o = (f32x4*)(yout + (size_t)row * DM) + lane;
; #pragma unroll
;         for (int j = 0; j < 4; ++j) o[64 * j] = v[j] * rstd * gv[j] + bv[j];
;     }
.LBB0_2458:
	global_load_dwordx2 v[80:81], v[32:33], off nt
	global_load_dwordx2 v[82:83], v[32:33], off offset:512 nt
	global_load_dwordx2 v[84:85], v[32:33], off offset:1024 nt
	global_load_dwordx2 v[86:87], v[32:33], off offset:1536 nt
	s_add_i32 s8, s8, s10
	v_lshl_add_u64 v[32:33], v[32:33], 0, s[2:3]
	s_cmpk_lt_i32 s8, 0x4080
	v_lshlrev_b32_e32 v53, 16, v45
	v_lshlrev_b32_e32 v52, 16, v44
	v_and_b32_e32 v45, 0xffff0000, v45
	v_and_b32_e32 v44, 0xffff0000, v44
	v_lshlrev_b32_e32 v55, 16, v47
	v_lshlrev_b32_e32 v54, 16, v46
	v_and_b32_e32 v47, 0xffff0000, v47
	v_and_b32_e32 v46, 0xffff0000, v46
	v_pk_add_f32 v[64:65], v[52:53], v[44:45]
	v_pk_add_f32 v[66:67], v[54:55], v[46:47]
	v_lshlrev_b32_e32 v56, 16, v48
	v_and_b32_e32 v57, 0xffff0000, v48
	v_lshlrev_b32_e32 v48, 16, v49
	v_and_b32_e32 v49, 0xffff0000, v49
	v_and_b32_e32 v61, 0xffff0000, v50
	v_add_f32_e32 v43, v64, v65
	v_pk_add_f32 v[64:65], v[66:67], v[66:67] op_sel:[0,1] op_sel_hi:[1,0]
	v_lshlrev_b32_e32 v59, 16, v50
	v_lshlrev_b32_e32 v63, 16, v51
	v_and_b32_e32 v51, 0xffff0000, v51
	v_add_f32_e32 v62, v56, v57
	v_add_f32_e32 v50, v48, v49
	v_add_f32_e32 v58, 0, v43
	v_mov_b32_e32 v65, v61
	v_pk_add_f32 v[66:67], v[62:63], v[50:51]
	v_pk_add_f32 v[64:65], v[58:59], v[64:65]
	s_nop 0
	v_pk_add_f32 v[64:65], v[64:65], v[66:67]
	s_nop 0
	v_add_f32_e32 v43, v64, v65
	ds_bpermute_b32 v50, v36, v43
	s_waitcnt lgkmcnt(0)
	v_add_f32_e32 v43, v43, v50
	ds_bpermute_b32 v50, v37, v43
	s_waitcnt lgkmcnt(0)
	v_add_f32_e32 v43, v43, v50
	ds_bpermute_b32 v50, v38, v43
	s_waitcnt lgkmcnt(0)
	v_add_f32_e32 v43, v43, v50
	ds_bpermute_b32 v50, v39, v43
	s_waitcnt lgkmcnt(0)
	v_add_f32_e32 v43, v43, v50
	ds_bpermute_b32 v50, v40, v43
	s_waitcnt lgkmcnt(0)
	v_add_f32_e32 v43, v43, v50
	ds_bpermute_b32 v50, v41, v43
	s_waitcnt lgkmcnt(0)
	v_add_f32_e32 v43, v43, v50
	v_fmac_f32_e32 v44, 0xba800000, v43
	v_fmac_f32_e32 v45, 0xba800000, v43
	v_fmac_f32_e32 v53, 0xba800000, v43
	v_fmac_f32_e32 v46, 0xba800000, v43
	v_fmac_f32_e32 v47, 0xba800000, v43
	v_fmac_f32_e32 v55, 0xba800000, v43
	v_fmac_f32_e32 v52, 0xba800000, v43
	v_fmac_f32_e32 v54, 0xba800000, v43
	v_fmac_f32_e32 v56, 0xba800000, v43
	v_mov_b32_e32 v64, v53
	v_mov_b32_e32 v65, v45
	v_mov_b32_e32 v53, v44
	v_mov_b32_e32 v44, v55
	v_mov_b32_e32 v45, v47
	v_mov_b32_e32 v55, v46
	v_fmac_f32_e32 v57, 0xba800000, v43
	v_fmac_f32_e32 v48, 0xba800000, v43
	v_mul_f32_e32 v46, v56, v56
	v_pk_mul_f32 v[66:67], v[64:65], v[64:65]
	v_pk_mul_f32 v[68:69], v[52:53], v[52:53]
	v_pk_mul_f32 v[70:71], v[44:45], v[44:45]
	v_pk_mul_f32 v[72:73], v[54:55], v[54:55]
	v_fmac_f32_e32 v49, 0xba800000, v43
	v_fmac_f32_e32 v59, 0xba800000, v43
	v_mul_f32_e32 v58, v48, v48
	v_pk_fma_f32 v[46:47], v[56:57], v[56:57], v[46:47] op_sel_hi:[1,1,0]
	v_pk_mov_b32 v[76:77], v[68:69], v[66:67] op_sel:[1,0]
	v_mov_b32_e32 v69, v67
	v_pk_mov_b32 v[66:67], v[72:73], v[70:71] op_sel:[1,0]
	v_mov_b32_e32 v73, v71
	v_mov_b32_e32 v60, v59
	v_pk_fma_f32 v[74:75], v[48:49], v[48:49], v[58:59] op_sel_hi:[1,1,0]
	v_mul_f32_e32 v46, v59, v59
	v_pk_add_f32 v[58:59], v[76:77], v[68:69]
	v_pk_add_f32 v[66:67], v[66:67], v[72:73]
	v_fmac_f32_e32 v51, 0xba800000, v43
	v_fmac_f32_e32 v63, 0xba800000, v43
	v_fmac_f32_e32 v61, 0xba800000, v43
	v_pk_add_f32 v[58:59], v[58:59], v[58:59] op_sel_hi:[0,1]
	v_pk_add_f32 v[66:67], v[66:67], v[66:67] op_sel_hi:[0,1]
	v_mul_f32_e32 v74, v61, v61
	v_mul_f32_e32 v58, v63, v63
	v_mul_f32_e32 v66, v51, v51
	v_pk_add_f32 v[46:47], v[46:47], v[74:75]
	v_pk_add_f32 v[58:59], v[58:59], v[66:67]
	v_mov_b32_e32 v50, v63
	v_pk_add_f32 v[46:47], v[46:47], v[58:59]
	s_nop 0
	v_add_f32_e32 v43, v46, v47
	ds_bpermute_b32 v46, v36, v43
	s_waitcnt lgkmcnt(0)
	v_add_f32_e32 v43, v43, v46
	ds_bpermute_b32 v46, v37, v43
	s_waitcnt lgkmcnt(0)
	v_add_f32_e32 v43, v43, v46
	ds_bpermute_b32 v46, v38, v43
	s_waitcnt lgkmcnt(0)
	v_add_f32_e32 v43, v43, v46
	ds_bpermute_b32 v46, v39, v43
	s_waitcnt lgkmcnt(0)
	v_add_f32_e32 v43, v43, v46
	ds_bpermute_b32 v46, v40, v43
	s_waitcnt lgkmcnt(0)
	v_add_f32_e32 v43, v43, v46
	ds_bpermute_b32 v46, v41, v43
	s_waitcnt lgkmcnt(0)
	v_add_f32_e32 v43, v43, v46
	v_fmamk_f32 v43, v43, 0x3a800000, v42
	v_rsq_f32_e32 v46, v43
	s_nop 0
	v_pk_mul_f32 v[52:53], v[52:53], v[46:47] op_sel_hi:[1,0]
	v_pk_mul_f32 v[58:59], v[64:65], v[46:47] op_sel_hi:[1,0]
	v_pk_mul_f32 v[54:55], v[54:55], v[46:47] op_sel_hi:[1,0]
	v_pk_mul_f32 v[62:63], v[44:45], v[46:47] op_sel_hi:[1,0]
	v_pk_mul_f32 v[56:57], v[56:57], v[46:47] op_sel_hi:[1,0]
	v_pk_mul_f32 v[64:65], v[48:49], v[46:47] op_sel_hi:[1,0]
	v_pk_mul_f32 v[60:61], v[60:61], v[46:47] op_sel_hi:[1,0]
	v_pk_mul_f32 v[66:67], v[50:51], v[46:47] op_sel_hi:[1,0]
	v_pk_fma_f32 v[46:47], v[2:3], v[58:59], v[6:7]
	v_pk_fma_f32 v[44:45], v[0:1], v[52:53], v[4:5]
	v_pk_fma_f32 v[50:51], v[10:11], v[62:63], v[18:19]
	v_pk_fma_f32 v[48:49], v[8:9], v[54:55], v[16:17]
	v_pk_fma_f32 v[54:55], v[14:15], v[64:65], v[22:23]
	v_pk_fma_f32 v[52:53], v[12:13], v[56:57], v[20:21]
	v_pk_fma_f32 v[58:59], v[26:27], v[66:67], v[30:31]
	v_pk_fma_f32 v[56:57], v[24:25], v[60:61], v[28:29]
	s_waitcnt vmcnt(0)
	global_store_dwordx4 v[34:35], v[44:47], off offset:-3072 sc1
	global_store_dwordx4 v[34:35], v[48:51], off offset:-2048 sc1
	global_store_dwordx4 v[34:35], v[52:55], off offset:-1024 sc1
	global_store_dwordx4 v[34:35], v[56:59], off sc1
	v_lshl_add_u64 v[34:35], v[34:35], 0, s[4:5]
	s_nop 1
	v_mov_b64_e32 v[44:45], v[80:81]
	v_mov_b64_e32 v[46:47], v[82:83]
	v_mov_b64_e32 v[48:49], v[84:85]
	v_mov_b64_e32 v[50:51], v[86:87]
	s_cbranch_scc1 .LBB0_2458
